# adds: hoisted ssq_in loads in MLP2/KV GEMM epilogues with counted waits; norm0 gain loads hoisted out of row loop; gla_prep v-tile loads batched (one wait instead of eight)
# speedup vs baseline: 1.0022x; 1.0022x over previous
.LBB0_55:
	v_mbcnt_hi_u32_b32 v2, -1, v1
	v_and_b32_e32 v3, 64, v2
	v_add_u32_e32 v3, 64, v3
	v_xor_b32_e32 v4, 1, v2
	v_cmp_lt_i32_e32 vcc, v4, v3
	s_mov_b64 s[12:13], 0x1400
	s_ashr_i32 s9, s8, 31
	v_cndmask_b32_e32 v4, v2, v4, vcc
	v_lshlrev_b32_e32 v38, 2, v4
	v_xor_b32_e32 v4, 2, v2
	v_cmp_lt_i32_e32 vcc, v4, v3
	s_mov_b64 s[10:11], 0x1000
	v_mov_b32_e32 v44, 0x358637bd
	v_cndmask_b32_e32 v4, v2, v4, vcc
	v_lshlrev_b32_e32 v39, 2, v4
	v_xor_b32_e32 v4, 4, v2
	v_cmp_lt_i32_e32 vcc, v4, v3
	s_mov_b32 s14, s8
	s_nop 0
	v_cndmask_b32_e32 v4, v2, v4, vcc
	v_lshlrev_b32_e32 v40, 2, v4
	v_xor_b32_e32 v4, 8, v2
	v_cmp_lt_i32_e32 vcc, v4, v3
	s_nop 1
	v_cndmask_b32_e32 v4, v2, v4, vcc
	v_lshlrev_b32_e32 v41, 2, v4
	v_xor_b32_e32 v4, 16, v2
	v_cmp_lt_i32_e32 vcc, v4, v3
	s_nop 1
	v_cndmask_b32_e32 v4, v2, v4, vcc
	v_lshlrev_b32_e32 v42, 2, v4
	v_xor_b32_e32 v4, 32, v2
	v_cmp_lt_i32_e32 vcc, v4, v3
	v_mov_b32_e32 v3, 0
	s_nop 0
	v_cndmask_b32_e32 v2, v2, v4, vcc
	v_lshlrev_b32_e32 v43, 2, v2
	v_lshlrev_b32_e32 v2, 4, v37
	v_lshl_add_u64 v[22:23], s[54:55], 0, v[2:3]
	v_lshl_add_u64 v[26:27], v[22:23], 0, s[12:13]
	s_mov_b64 s[12:13], 0x1800
	v_lshl_add_u64 v[28:29], v[22:23], 0, s[12:13]
	s_mov_b64 s[12:13], 0x1c00
	v_lshl_add_u64 v[30:31], v[22:23], 0, s[12:13]
	s_lshl_b64 s[12:13], s[8:9], 13
	s_add_u32 s12, s52, s12
	s_addc_u32 s13, s53, s13
	v_lshl_add_u64 v[4:5], s[12:13], 0, v[2:3]
	s_ashr_i32 s87, s86, 31
	v_lshl_add_u64 v[24:25], v[22:23], 0, s[10:11]
	v_lshl_add_u64 v[32:33], v[4:5], 0, s[10:11]
	s_lshl_b64 s[10:11], s[86:87], 13
	s_lshl_b64 s[12:13], s[8:9], 12
	s_add_u32 s12, s0, s12
	v_lshlrev_b32_e32 v2, 3, v37
	s_addc_u32 s13, s1, s13
	v_lshl_add_u64 v[2:3], s[12:13], 0, v[2:3]
	s_mov_b64 s[12:13], 0x17400000
	v_lshl_add_u64 v[34:35], v[2:3], 0, s[12:13]
	s_lshl_b64 s[12:13], s[86:87], 12
	s_brev_b32 s9, 64
	global_load_dwordx4 v[104:107], v[22:23], off
	global_load_dwordx4 v[108:111], v[22:23], off offset:1024
	global_load_dwordx4 v[112:115], v[22:23], off offset:2048
	global_load_dwordx4 v[116:119], v[22:23], off offset:3072
	global_load_dwordx4 v[120:123], v[24:25], off
	global_load_dwordx4 v[124:127], v[26:27], off
	global_load_dwordx4 v[128:131], v[28:29], off
	global_load_dwordx4 v[132:135], v[30:31], off
.LBB0_56:
	global_load_dwordx4 v[46:49], v[32:33], off offset:-4096
	global_load_dwordx4 v[50:53], v[32:33], off offset:-3072
	global_load_dwordx4 v[54:57], v[32:33], off offset:-2048
	global_load_dwordx4 v[18:21], v[32:33], off offset:-1024
	global_load_dwordx4 v[14:17], v[32:33], off
	global_load_dwordx4 v[10:13], v[32:33], off offset:1024
	global_load_dwordx4 v[6:9], v[32:33], off offset:2048
	global_load_dwordx4 v[2:5], v[32:33], off offset:3072
	v_add_co_u32_e32 v58, vcc, s9, v34
	s_add_i32 s14, s14, s86
	s_nop 0
	v_addc_co_u32_e32 v59, vcc, 0, v35, vcc
	v_lshl_add_u64 v[32:33], v[32:33], 0, s[10:11]
	s_cmpk_gt_i32 s14, 0x1fff
	s_waitcnt vmcnt(0)
	v_cvt_pk_bf16_f32 v60, v46, v47
	v_cvt_pk_bf16_f32 v61, v48, v49
	v_cvt_pk_bf16_f32 v62, v50, v51
	v_cvt_pk_bf16_f32 v63, v52, v53
	v_cvt_pk_bf16_f32 v64, v54, v55
	v_cvt_pk_bf16_f32 v65, v56, v57
	v_cvt_pk_bf16_f32 v66, v18, v19
	v_cvt_pk_bf16_f32 v67, v20, v21
	v_cvt_pk_bf16_f32 v68, v14, v15
	v_cvt_pk_bf16_f32 v69, v16, v17
	v_cvt_pk_bf16_f32 v70, v10, v11
	v_cvt_pk_bf16_f32 v71, v12, v13
	v_cvt_pk_bf16_f32 v72, v6, v7
	v_cvt_pk_bf16_f32 v73, v8, v9
	v_cvt_pk_bf16_f32 v74, v2, v3
	v_cvt_pk_bf16_f32 v75, v4, v5
	flat_store_dwordx2 v[58:59], v[60:61]
	flat_store_dwordx2 v[58:59], v[62:63] offset:512
	flat_store_dwordx2 v[58:59], v[64:65] offset:1024
	flat_store_dwordx2 v[58:59], v[66:67] offset:1536
	flat_store_dwordx2 v[58:59], v[68:69] offset:2048
	flat_store_dwordx2 v[58:59], v[70:71] offset:2560
	flat_store_dwordx2 v[58:59], v[72:73] offset:3072
	flat_store_dwordx2 v[58:59], v[74:75] offset:3584
	v_mov_b32_e32 v58, v104
	v_mov_b32_e32 v59, v105
	v_mov_b32_e32 v60, v106
	v_mov_b32_e32 v61, v107
	v_mov_b32_e32 v78, v47
	v_mov_b32_e32 v79, v51
	v_mov_b32_e32 v82, v49
	v_mov_b32_e32 v83, v53
	v_mov_b32_e32 v76, v46
	v_mov_b32_e32 v77, v50
	v_mov_b32_e32 v80, v48
	v_mov_b32_e32 v81, v52
	v_pk_mul_f32 v[84:85], v[56:57], v[56:57]
	v_pk_mul_f32 v[86:87], v[54:55], v[54:55]
	v_pk_mul_f32 v[62:63], v[78:79], v[78:79]
	v_pk_mul_f32 v[64:65], v[82:83], v[82:83]
	v_pk_mov_b32 v[66:67], v[86:87], v[84:85] op_sel:[1,0]
	v_mov_b32_e32 v87, v85
	v_pk_fma_f32 v[62:63], v[76:77], v[76:77], v[62:63]
	v_pk_fma_f32 v[64:65], v[80:81], v[80:81], v[64:65]
	v_mul_f32_e32 v89, v15, v15
	v_mul_f32_e32 v91, v16, v16
	v_mul_f32_e32 v88, v19, v19
	v_mul_f32_e32 v90, v21, v21
	v_pk_add_f32 v[66:67], v[66:67], v[86:87]
	v_pk_add_f32 v[62:63], v[62:63], v[64:65]
	v_mul_f32_e32 v45, v14, v14
	v_mul_f32_e32 v97, v17, v17
	v_pk_fma_f32 v[68:69], v[18:19], v[18:19], v[88:89] op_sel_hi:[1,1,0]
	v_pk_fma_f32 v[70:71], v[20:21], v[20:21], v[90:91] op_sel_hi:[1,1,0]
	v_pk_add_f32 v[64:65], v[66:67], v[66:67] op_sel:[0,1] op_sel_hi:[1,0]
	v_pk_add_f32 v[62:63], v[62:63], v[62:63] op_sel:[0,1] op_sel_hi:[1,0]
	v_pk_mul_f32 v[92:93], v[12:13], v[12:13]
	v_pk_mul_f32 v[94:95], v[10:11], v[10:11]
	v_mov_b32_e32 v69, v91
	v_mov_b32_e32 v71, v97
	v_mov_b32_e32 v65, v89
	v_mov_b32_e32 v63, v45
	v_pk_mov_b32 v[72:73], v[94:95], v[92:93] op_sel:[1,0]
	v_mov_b32_e32 v95, v93
	v_pk_add_f32 v[66:67], v[68:69], v[70:71]
	v_pk_add_f32 v[62:63], v[62:63], v[64:65]
	v_mul_f32_e32 v99, v2, v2
	v_mul_f32_e32 v96, v7, v7
	v_mul_f32_e32 v98, v9, v9
	v_pk_add_f32 v[72:73], v[72:73], v[94:95]
	v_pk_add_f32 v[62:63], v[62:63], v[66:67]
	v_mul_f32_e32 v100, v3, v3
	v_mul_f32_e32 v101, v4, v4
	v_mul_f32_e32 v102, v5, v5
	v_pk_fma_f32 v[74:75], v[6:7], v[6:7], v[96:97] op_sel_hi:[1,1,0]
	v_pk_fma_f32 v[78:79], v[8:9], v[8:9], v[98:99] op_sel_hi:[1,1,0]
	v_pk_add_f32 v[68:69], v[72:73], v[72:73] op_sel:[0,1] op_sel_hi:[1,0]
	v_pk_add_f32 v[62:63], v[62:63], v[62:63] op_sel:[0,1] op_sel_hi:[1,0]
	v_mov_b32_e32 v75, v101
	v_mov_b32_e32 v79, v102
	v_mov_b32_e32 v69, v100
	v_mov_b32_e32 v63, v99
	v_pk_add_f32 v[70:71], v[74:75], v[78:79]
	v_pk_add_f32 v[62:63], v[62:63], v[68:69]
	s_nop 0
	v_pk_add_f32 v[62:63], v[62:63], v[70:71]
	s_nop 0
	v_add_f32_e32 v45, v62, v63
	ds_bpermute_b32 v62, v38, v45
	s_waitcnt lgkmcnt(0)
	v_add_f32_e32 v45, v45, v62
	ds_bpermute_b32 v62, v39, v45
	s_waitcnt lgkmcnt(0)
	v_add_f32_e32 v45, v45, v62
	ds_bpermute_b32 v62, v40, v45
	s_waitcnt lgkmcnt(0)
	v_add_f32_e32 v45, v45, v62
	ds_bpermute_b32 v62, v41, v45
	s_waitcnt lgkmcnt(0)
	v_add_f32_e32 v45, v45, v62
	ds_bpermute_b32 v62, v42, v45
	s_waitcnt lgkmcnt(0)
	v_add_f32_e32 v45, v45, v62
	ds_bpermute_b32 v62, v43, v45
	s_waitcnt lgkmcnt(0)
	v_add_f32_e32 v45, v45, v62
	v_fmamk_f32 v45, v45, 0x3a000000, v44
	v_rsq_f32_e32 v62, v45
	s_nop 0
	v_pk_mul_f32 v[46:47], v[46:47], v[62:63] op_sel_hi:[1,0]
	v_pk_mul_f32 v[48:49], v[48:49], v[62:63] op_sel_hi:[1,0]
	s_nop 0
	v_pk_mul_f32 v[46:47], v[58:59], v[46:47]
	v_pk_mul_f32 v[48:49], v[60:61], v[48:49]
	v_cvt_pk_bf16_f32 v46, v46, v47
	v_cvt_pk_bf16_f32 v47, v48, v49
	flat_store_dwordx2 v[34:35], v[46:47]
	v_mov_b32_e32 v46, v108
	v_mov_b32_e32 v47, v109
	v_mov_b32_e32 v48, v110
	v_mov_b32_e32 v49, v111
	v_pk_mul_f32 v[50:51], v[50:51], v[62:63] op_sel_hi:[1,0]
	v_pk_mul_f32 v[52:53], v[52:53], v[62:63] op_sel_hi:[1,0]
	v_pk_mul_f32 v[18:19], v[18:19], v[62:63] op_sel_hi:[1,0]
	v_pk_mul_f32 v[20:21], v[20:21], v[62:63] op_sel_hi:[1,0]
	v_pk_mul_f32 v[14:15], v[14:15], v[62:63] op_sel_hi:[1,0]
	v_pk_mul_f32 v[16:17], v[16:17], v[62:63] op_sel_hi:[1,0]
	v_pk_mul_f32 v[10:11], v[10:11], v[62:63] op_sel_hi:[1,0]
	v_pk_mul_f32 v[12:13], v[12:13], v[62:63] op_sel_hi:[1,0]
	v_pk_mul_f32 v[6:7], v[6:7], v[62:63] op_sel_hi:[1,0]
	v_pk_mul_f32 v[8:9], v[8:9], v[62:63] op_sel_hi:[1,0]
	v_pk_mul_f32 v[2:3], v[2:3], v[62:63] op_sel_hi:[1,0]
	v_pk_mul_f32 v[4:5], v[4:5], v[62:63] op_sel_hi:[1,0]
	s_nop 0
	v_pk_mul_f32 v[48:49], v[48:49], v[52:53]
	v_pk_mul_f32 v[46:47], v[46:47], v[50:51]
	v_pk_mul_f32 v[50:51], v[54:55], v[62:63] op_sel_hi:[1,0]
	v_cvt_pk_bf16_f32 v46, v46, v47
	v_cvt_pk_bf16_f32 v47, v48, v49
	flat_store_dwordx2 v[34:35], v[46:47] offset:512
	v_mov_b32_e32 v46, v112
	v_mov_b32_e32 v47, v113
	v_mov_b32_e32 v48, v114
	v_mov_b32_e32 v49, v115
	v_pk_mul_f32 v[52:53], v[56:57], v[62:63] op_sel_hi:[1,0]
	s_nop 0
	v_pk_mul_f32 v[46:47], v[46:47], v[50:51]
	v_pk_mul_f32 v[48:49], v[48:49], v[52:53]
	v_cvt_pk_bf16_f32 v46, v46, v47
	v_cvt_pk_bf16_f32 v47, v48, v49
	flat_store_dwordx2 v[34:35], v[46:47] offset:1024
	v_mov_b32_e32 v46, v116
	v_mov_b32_e32 v47, v117
	v_mov_b32_e32 v48, v118
	v_mov_b32_e32 v49, v119
	s_nop 0
	v_pk_mul_f32 v[20:21], v[48:49], v[20:21]
	v_pk_mul_f32 v[18:19], v[46:47], v[18:19]
	s_nop 0
	v_cvt_pk_bf16_f32 v18, v18, v19
	v_cvt_pk_bf16_f32 v19, v20, v21
	flat_store_dwordx2 v[34:35], v[18:19] offset:1536
	v_mov_b32_e32 v18, v120
	v_mov_b32_e32 v19, v121
	v_mov_b32_e32 v20, v122
	v_mov_b32_e32 v21, v123
	s_nop 0
	v_pk_mul_f32 v[16:17], v[16:17], v[20:21]
	v_pk_mul_f32 v[14:15], v[14:15], v[18:19]
	s_nop 0
	v_cvt_pk_bf16_f32 v14, v14, v15
	v_cvt_pk_bf16_f32 v15, v16, v17
	flat_store_dwordx2 v[34:35], v[14:15] offset:2048
	v_mov_b32_e32 v14, v124
	v_mov_b32_e32 v15, v125
	v_mov_b32_e32 v16, v126
	v_mov_b32_e32 v17, v127
	s_nop 0
	v_pk_mul_f32 v[12:13], v[12:13], v[16:17]
	v_pk_mul_f32 v[10:11], v[10:11], v[14:15]
	s_nop 0
	v_cvt_pk_bf16_f32 v10, v10, v11
	v_cvt_pk_bf16_f32 v11, v12, v13
	flat_store_dwordx2 v[34:35], v[10:11] offset:2560
	v_mov_b32_e32 v10, v128
	v_mov_b32_e32 v11, v129
	v_mov_b32_e32 v12, v130
	v_mov_b32_e32 v13, v131
	s_nop 0
	v_pk_mul_f32 v[8:9], v[8:9], v[12:13]
	v_pk_mul_f32 v[6:7], v[6:7], v[10:11]
	s_nop 0
	v_cvt_pk_bf16_f32 v6, v6, v7
	v_cvt_pk_bf16_f32 v7, v8, v9
	flat_store_dwordx2 v[34:35], v[6:7] offset:3072
	v_mov_b32_e32 v6, v132
	v_mov_b32_e32 v7, v133
	v_mov_b32_e32 v8, v134
	v_mov_b32_e32 v9, v135
	s_nop 0
	v_pk_mul_f32 v[4:5], v[4:5], v[8:9]
	v_pk_mul_f32 v[2:3], v[2:3], v[6:7]
	s_nop 0
	v_cvt_pk_bf16_f32 v2, v2, v3
	v_cvt_pk_bf16_f32 v3, v4, v5
	flat_store_dwordx2 v[34:35], v[2:3] offset:3584
	v_lshl_add_u64 v[34:35], v[34:35], 0, s[12:13]
	s_cbranch_scc0 .LBB0_56

.LBB0_179:
	v_lshl_add_u32 v142, s0, 8, v144
	v_ashrrev_i32_e32 v143, 31, v142
	v_lshlrev_b64 v[140:141], 7, v[142:143]
	v_lshl_add_u64 v[140:141], v[134:135], 0, v[140:141]
	global_load_dwordx4 v[172:175], v[140:141], off
	global_load_dwordx4 v[176:179], v[140:141], off offset:16
	global_load_dwordx4 v[180:183], v[140:141], off offset:2048
	global_load_dwordx4 v[184:187], v[140:141], off offset:2064
	v_add_co_u32_e32 v248, vcc, 0x1000, v140
	s_nop 1
	v_addc_co_u32_e32 v249, vcc, 0, v141, vcc
	global_load_dwordx4 v[188:191], v[248:249], off
	global_load_dwordx4 v[198:201], v[248:249], off offset:16
	global_load_dwordx4 v[202:205], v[248:249], off offset:2048
	global_load_dwordx4 v[206:209], v[248:249], off offset:2064
	v_add_co_u32_e32 v248, vcc, 0x3000, v248
	s_nop 1
	v_addc_co_u32_e32 v249, vcc, 0, v249, vcc
	global_load_dwordx4 v[210:213], v[248:249], off
	global_load_dwordx4 v[214:217], v[248:249], off offset:16
	global_load_dwordx4 v[218:221], v[248:249], off offset:2048
	global_load_dwordx4 v[222:225], v[248:249], off offset:2064
	v_add_co_u32_e32 v248, vcc, 0x1000, v248
	s_nop 1
	v_addc_co_u32_e32 v249, vcc, 0, v249, vcc
	global_load_dwordx4 v[226:229], v[248:249], off
	global_load_dwordx4 v[230:233], v[248:249], off offset:16
	global_load_dwordx4 v[240:243], v[248:249], off offset:2048
	global_load_dwordx4 v[244:247], v[248:249], off offset:2064
	s_nop 0
	v_and_b32_e32 v148, 64, v236
	v_xor_b32_e32 v141, 16, v236
	v_add_u32_e32 v170, 64, v148
	v_cmp_lt_i32_e32 vcc, v141, v170
	v_xor_b32_e32 v149, 32, v236
	v_lshl_or_b32 v140, s1, 8, v147
	v_cndmask_b32_e32 v141, v236, v141, vcc
	v_lshlrev_b32_e32 v148, 2, v141
	v_cmp_lt_i32_e32 vcc, v149, v170
	v_ashrrev_i32_e32 v141, 31, v140
	v_lshlrev_b64 v[140:141], 1, v[140:141]
	v_cndmask_b32_e32 v149, v236, v149, vcc
	v_lshlrev_b32_e32 v149, 2, v149
	s_waitcnt vmcnt(14) lgkmcnt(0)
	v_mov_b32_e32 v150, v172
	v_mov_b32_e32 v151, v173
	v_mov_b32_e32 v152, v174
	v_mov_b32_e32 v153, v175
	v_mov_b32_e32 v154, v176
	v_mov_b32_e32 v155, v177
	v_mov_b32_e32 v156, v178
	v_mov_b32_e32 v157, v179
	v_mov_b32_e32 v158, v150
	v_mov_b32_e32 v159, v154
	v_mov_b32_e32 v154, v151
	v_mov_b32_e32 v150, v152
	v_mov_b32_e32 v151, v156
	v_mov_b32_e32 v156, v153
	v_pk_add_f32 v[152:153], v[158:159], v[154:155]
	v_pk_add_f32 v[150:151], v[150:151], v[156:157]
	s_nop 0
	v_pk_add_f32 v[150:151], v[152:153], v[150:151]
	v_lshlrev_b64 v[152:153], 10, v[142:143]
	v_add_f32_e32 v150, v150, v151
	ds_bpermute_b32 v151, v148, v150
	v_lshl_add_u64 v[152:153], s[6:7], 0, v[152:153]
	v_lshl_add_u64 v[152:153], v[152:153], 0, v[140:141]
	s_waitcnt lgkmcnt(0)
	v_add_f32_e32 v154, v150, v151
	ds_bpermute_b32 v155, v149, v154
	v_or_b32_e32 v150, 16, v142
	v_ashrrev_i32_e32 v151, 31, v150
	s_waitcnt lgkmcnt(0)
	v_add_f32_e32 v143, v154, v155
	v_fmamk_f32 v143, v143, 0x3a000000, v195
	v_mul_f32_e32 v154, 0x4f800000, v143
	v_cmp_gt_f32_e32 vcc, s48, v143
	s_nop 1
	v_cndmask_b32_e32 v143, v143, v154, vcc
	v_sqrt_f32_e32 v156, v143
	v_lshlrev_b64 v[154:155], 7, v[150:151]
	v_lshl_add_u64 v[154:155], v[134:135], 0, v[154:155]
	v_add_u32_e32 v157, -1, v156
	v_add_u32_e32 v158, 1, v156
	v_fma_f32 v159, -v157, v156, v143
	v_fma_f32 v170, -v158, v156, v143
	v_cmp_ge_f32_e64 s[0:1], 0, v159
	s_nop 1
	v_cndmask_b32_e64 v156, v156, v157, s[0:1]
	v_cmp_lt_f32_e64 s[0:1], 0, v170
	s_nop 1
	v_cndmask_b32_e64 v156, v156, v158, s[0:1]
	v_mul_f32_e32 v157, 0x37800000, v156
	v_cndmask_b32_e32 v156, v156, v157, vcc
	v_cmp_class_f32_e32 vcc, v143, v197
	s_nop 1
	v_cndmask_b32_e32 v143, v156, v143, vcc
	v_div_scale_f32 v156, s[0:1], v143, v143, 1.0
	v_rcp_f32_e32 v157, v156
	v_div_scale_f32 v158, vcc, 1.0, v143, 1.0
	v_fma_f32 v159, -v156, v157, 1.0
	v_fmac_f32_e32 v157, v159, v157
	v_mul_f32_e32 v159, v158, v157
	v_fma_f32 v170, -v156, v159, v158
	v_fmac_f32_e32 v159, v170, v157
	v_fma_f32 v156, -v156, v159, v158
	v_div_fmas_f32 v156, v156, v157, v159
	v_div_fixup_f32 v156, v156, v143, 1.0
	v_pk_mul_f32 v[126:127], v[126:127], v[156:157] op_sel_hi:[1,0]
	v_pk_mul_f32 v[124:125], v[124:125], v[156:157] op_sel_hi:[1,0]
	v_pk_mul_f32 v[122:123], v[122:123], v[156:157] op_sel_hi:[1,0]
	v_pk_mul_f32 v[120:121], v[120:121], v[156:157] op_sel_hi:[1,0]
	v_pk_mul_f32 v[118:119], v[118:119], v[156:157] op_sel_hi:[1,0]
	v_pk_mul_f32 v[116:117], v[116:117], v[156:157] op_sel_hi:[1,0]
	v_pk_mul_f32 v[158:159], v[114:115], v[156:157] op_sel_hi:[1,0]
	v_pk_mul_f32 v[156:157], v[112:113], v[156:157] op_sel_hi:[1,0]
	v_cvt_pk_bf16_f32 v112, v124, v125
	v_cvt_pk_bf16_f32 v113, v126, v127
	v_cvt_pk_bf16_f32 v114, v120, v121
	v_cvt_pk_bf16_f32 v115, v122, v123
	flat_store_dwordx4 v[152:153], v[112:115]
	s_nop 1
	v_cvt_pk_bf16_f32 v112, v116, v117
	v_cvt_pk_bf16_f32 v113, v118, v119
	v_cvt_pk_bf16_f32 v114, v156, v157
	v_cvt_pk_bf16_f32 v115, v158, v159
	flat_store_dwordx4 v[152:153], v[112:115] offset:256
	s_nop 0
	s_nop 0
	s_nop 0
	s_waitcnt vmcnt(14) lgkmcnt(0)
	v_mov_b32_e32 v112, v180
	v_mov_b32_e32 v113, v181
	v_mov_b32_e32 v114, v182
	v_mov_b32_e32 v115, v183
	v_mov_b32_e32 v116, v184
	v_mov_b32_e32 v117, v185
	v_mov_b32_e32 v118, v186
	v_mov_b32_e32 v119, v187
	v_mov_b32_e32 v120, v112
	v_mov_b32_e32 v121, v116
	v_mov_b32_e32 v116, v113
	v_mov_b32_e32 v112, v114
	v_mov_b32_e32 v113, v118
	v_mov_b32_e32 v118, v115
	v_pk_add_f32 v[114:115], v[120:121], v[116:117]
	v_pk_add_f32 v[112:113], v[112:113], v[118:119]
	s_nop 0
	v_pk_add_f32 v[112:113], v[114:115], v[112:113]
	v_lshlrev_b64 v[114:115], 10, v[150:151]
	v_add_f32_e32 v112, v112, v113
	ds_bpermute_b32 v113, v148, v112
	v_lshl_add_u64 v[114:115], s[6:7], 0, v[114:115]
	v_lshl_add_u64 v[114:115], v[114:115], 0, v[140:141]
	s_waitcnt lgkmcnt(0)
	v_add_f32_e32 v116, v112, v113
	ds_bpermute_b32 v117, v149, v116
	v_or_b32_e32 v112, 32, v142
	v_ashrrev_i32_e32 v113, 31, v112
	s_waitcnt lgkmcnt(0)
	v_add_f32_e32 v116, v116, v117
	v_fmamk_f32 v116, v116, 0x3a000000, v195
	v_mul_f32_e32 v117, 0x4f800000, v116
	v_cmp_gt_f32_e32 vcc, s48, v116
	s_nop 1
	v_cndmask_b32_e32 v118, v116, v117, vcc
	v_sqrt_f32_e32 v119, v118
	v_lshlrev_b64 v[116:117], 7, v[112:113]
	v_lshl_add_u64 v[116:117], v[134:135], 0, v[116:117]
	v_add_u32_e32 v120, -1, v119
	v_add_u32_e32 v121, 1, v119
	v_fma_f32 v122, -v120, v119, v118
	v_fma_f32 v123, -v121, v119, v118
	v_cmp_ge_f32_e64 s[0:1], 0, v122
	s_nop 1
	v_cndmask_b32_e64 v119, v119, v120, s[0:1]
	v_cmp_lt_f32_e64 s[0:1], 0, v123
	s_nop 1
	v_cndmask_b32_e64 v119, v119, v121, s[0:1]
	v_mul_f32_e32 v120, 0x37800000, v119
	v_cndmask_b32_e32 v119, v119, v120, vcc
	v_cmp_class_f32_e32 vcc, v118, v197
	s_nop 1
	v_cndmask_b32_e32 v118, v119, v118, vcc
	v_div_scale_f32 v119, s[0:1], v118, v118, 1.0
	v_rcp_f32_e32 v120, v119
	v_div_scale_f32 v121, vcc, 1.0, v118, 1.0
	v_fma_f32 v122, -v119, v120, 1.0
	v_fmac_f32_e32 v120, v122, v120
	v_mul_f32_e32 v122, v121, v120
	v_fma_f32 v123, -v119, v122, v121
	v_fmac_f32_e32 v122, v123, v120
	v_fma_f32 v119, -v119, v122, v121
	v_div_fmas_f32 v119, v119, v120, v122
	v_div_fixup_f32 v118, v119, v118, 1.0
	v_pk_mul_f32 v[110:111], v[110:111], v[118:119] op_sel_hi:[1,0]
	v_pk_mul_f32 v[108:109], v[108:109], v[118:119] op_sel_hi:[1,0]
	v_pk_mul_f32 v[106:107], v[106:107], v[118:119] op_sel_hi:[1,0]
	v_pk_mul_f32 v[104:105], v[104:105], v[118:119] op_sel_hi:[1,0]
	v_pk_mul_f32 v[102:103], v[102:103], v[118:119] op_sel_hi:[1,0]
	v_pk_mul_f32 v[100:101], v[100:101], v[118:119] op_sel_hi:[1,0]
	v_pk_mul_f32 v[120:121], v[98:99], v[118:119] op_sel_hi:[1,0]
	v_pk_mul_f32 v[118:119], v[96:97], v[118:119] op_sel_hi:[1,0]
	v_cvt_pk_bf16_f32 v96, v108, v109
	v_cvt_pk_bf16_f32 v97, v110, v111
	v_cvt_pk_bf16_f32 v98, v104, v105
	v_cvt_pk_bf16_f32 v99, v106, v107
	flat_store_dwordx4 v[114:115], v[96:99]
	s_nop 1
	v_cvt_pk_bf16_f32 v96, v100, v101
	v_cvt_pk_bf16_f32 v97, v102, v103
	v_cvt_pk_bf16_f32 v98, v118, v119
	v_cvt_pk_bf16_f32 v99, v120, v121
	flat_store_dwordx4 v[114:115], v[96:99] offset:256
	s_nop 0
	s_nop 0
	s_nop 0
	s_waitcnt vmcnt(14) lgkmcnt(0)
	v_mov_b32_e32 v96, v188
	v_mov_b32_e32 v97, v189
	v_mov_b32_e32 v98, v190
	v_mov_b32_e32 v99, v191
	v_mov_b32_e32 v100, v198
	v_mov_b32_e32 v101, v199
	v_mov_b32_e32 v102, v200
	v_mov_b32_e32 v103, v201
	v_mov_b32_e32 v104, v96
	v_mov_b32_e32 v105, v100
	v_mov_b32_e32 v100, v97
	v_mov_b32_e32 v96, v98
	v_mov_b32_e32 v97, v102
	v_mov_b32_e32 v102, v99
	v_pk_add_f32 v[98:99], v[104:105], v[100:101]
	v_pk_add_f32 v[96:97], v[96:97], v[102:103]
	s_nop 0
	v_pk_add_f32 v[96:97], v[98:99], v[96:97]
	v_lshlrev_b64 v[98:99], 10, v[112:113]
	v_add_f32_e32 v96, v96, v97
	ds_bpermute_b32 v97, v148, v96
	v_lshl_add_u64 v[98:99], s[6:7], 0, v[98:99]
	v_lshl_add_u64 v[98:99], v[98:99], 0, v[140:141]
	s_waitcnt lgkmcnt(0)
	v_add_f32_e32 v100, v96, v97
	ds_bpermute_b32 v101, v149, v100
	v_or_b32_e32 v96, 48, v142
	v_ashrrev_i32_e32 v97, 31, v96
	s_waitcnt lgkmcnt(0)
	v_add_f32_e32 v100, v100, v101
	v_fmamk_f32 v100, v100, 0x3a000000, v195
	v_mul_f32_e32 v101, 0x4f800000, v100
	v_cmp_gt_f32_e32 vcc, s48, v100
	s_nop 1
	v_cndmask_b32_e32 v102, v100, v101, vcc
	v_sqrt_f32_e32 v103, v102
	v_lshlrev_b64 v[100:101], 7, v[96:97]
	v_lshl_add_u64 v[100:101], v[134:135], 0, v[100:101]
	v_add_u32_e32 v104, -1, v103
	v_add_u32_e32 v105, 1, v103
	v_fma_f32 v106, -v104, v103, v102
	v_fma_f32 v107, -v105, v103, v102
	v_cmp_ge_f32_e64 s[0:1], 0, v106
	s_nop 1
	v_cndmask_b32_e64 v103, v103, v104, s[0:1]
	v_cmp_lt_f32_e64 s[0:1], 0, v107
	s_nop 1
	v_cndmask_b32_e64 v103, v103, v105, s[0:1]
	v_mul_f32_e32 v104, 0x37800000, v103
	v_cndmask_b32_e32 v103, v103, v104, vcc
	v_cmp_class_f32_e32 vcc, v102, v197
	s_nop 1
	v_cndmask_b32_e32 v102, v103, v102, vcc
	v_div_scale_f32 v103, s[0:1], v102, v102, 1.0
	v_rcp_f32_e32 v104, v103
	v_div_scale_f32 v105, vcc, 1.0, v102, 1.0
	v_fma_f32 v106, -v103, v104, 1.0
	v_fmac_f32_e32 v104, v106, v104
	v_mul_f32_e32 v106, v105, v104
	v_fma_f32 v107, -v103, v106, v105
	v_fmac_f32_e32 v106, v107, v104
	v_fma_f32 v103, -v103, v106, v105
	v_div_fmas_f32 v103, v103, v104, v106
	v_div_fixup_f32 v102, v103, v102, 1.0
	v_pk_mul_f32 v[94:95], v[94:95], v[102:103] op_sel_hi:[1,0]
	v_pk_mul_f32 v[92:93], v[92:93], v[102:103] op_sel_hi:[1,0]
	v_pk_mul_f32 v[90:91], v[90:91], v[102:103] op_sel_hi:[1,0]
	v_pk_mul_f32 v[88:89], v[88:89], v[102:103] op_sel_hi:[1,0]
	v_pk_mul_f32 v[86:87], v[86:87], v[102:103] op_sel_hi:[1,0]
	v_pk_mul_f32 v[84:85], v[84:85], v[102:103] op_sel_hi:[1,0]
	v_pk_mul_f32 v[104:105], v[82:83], v[102:103] op_sel_hi:[1,0]
	v_pk_mul_f32 v[102:103], v[80:81], v[102:103] op_sel_hi:[1,0]
	v_cvt_pk_bf16_f32 v80, v92, v93
	v_cvt_pk_bf16_f32 v81, v94, v95
	v_cvt_pk_bf16_f32 v82, v88, v89
	v_cvt_pk_bf16_f32 v83, v90, v91
	flat_store_dwordx4 v[98:99], v[80:83]
	s_nop 1
	v_cvt_pk_bf16_f32 v80, v84, v85
	v_cvt_pk_bf16_f32 v81, v86, v87
	v_cvt_pk_bf16_f32 v82, v102, v103
	v_cvt_pk_bf16_f32 v83, v104, v105
	flat_store_dwordx4 v[98:99], v[80:83] offset:256
	s_nop 0
	s_nop 0
	s_nop 0
	s_waitcnt vmcnt(14) lgkmcnt(0)
	v_mov_b32_e32 v80, v202
	v_mov_b32_e32 v81, v203
	v_mov_b32_e32 v82, v204
	v_mov_b32_e32 v83, v205
	v_mov_b32_e32 v84, v206
	v_mov_b32_e32 v85, v207
	v_mov_b32_e32 v86, v208
	v_mov_b32_e32 v87, v209
	v_mov_b32_e32 v88, v80
	v_mov_b32_e32 v89, v84
	v_mov_b32_e32 v84, v81
	v_mov_b32_e32 v80, v82
	v_mov_b32_e32 v81, v86
	v_mov_b32_e32 v86, v83
	v_pk_add_f32 v[82:83], v[88:89], v[84:85]
	v_pk_add_f32 v[80:81], v[80:81], v[86:87]
	s_nop 0
	v_pk_add_f32 v[80:81], v[82:83], v[80:81]
	v_lshlrev_b64 v[82:83], 10, v[96:97]
	v_add_f32_e32 v80, v80, v81
	ds_bpermute_b32 v81, v148, v80
	v_lshl_add_u64 v[82:83], s[6:7], 0, v[82:83]
	v_lshl_add_u64 v[82:83], v[82:83], 0, v[140:141]
	s_waitcnt lgkmcnt(0)
	v_add_f32_e32 v84, v80, v81
	ds_bpermute_b32 v85, v149, v84
	v_add_u32_e32 v80, 0x80, v142
	v_ashrrev_i32_e32 v81, 31, v80
	s_waitcnt lgkmcnt(0)
	v_add_f32_e32 v84, v84, v85
	v_fmamk_f32 v84, v84, 0x3a000000, v195
	v_mul_f32_e32 v85, 0x4f800000, v84
	v_cmp_gt_f32_e32 vcc, s48, v84
	s_nop 1
	v_cndmask_b32_e32 v86, v84, v85, vcc
	v_sqrt_f32_e32 v87, v86
	v_lshlrev_b64 v[84:85], 7, v[80:81]
	v_lshl_add_u64 v[84:85], v[134:135], 0, v[84:85]
	v_add_u32_e32 v88, -1, v87
	v_add_u32_e32 v89, 1, v87
	v_fma_f32 v90, -v88, v87, v86
	v_fma_f32 v91, -v89, v87, v86
	v_cmp_ge_f32_e64 s[0:1], 0, v90
	s_nop 1
	v_cndmask_b32_e64 v87, v87, v88, s[0:1]
	v_cmp_lt_f32_e64 s[0:1], 0, v91
	s_nop 1
	v_cndmask_b32_e64 v87, v87, v89, s[0:1]
	v_mul_f32_e32 v88, 0x37800000, v87
	v_cndmask_b32_e32 v87, v87, v88, vcc
	v_cmp_class_f32_e32 vcc, v86, v197
	s_nop 1
	v_cndmask_b32_e32 v86, v87, v86, vcc
	v_div_scale_f32 v87, s[0:1], v86, v86, 1.0
	v_rcp_f32_e32 v88, v87
	v_div_scale_f32 v89, vcc, 1.0, v86, 1.0
	v_fma_f32 v90, -v87, v88, 1.0
	v_fmac_f32_e32 v88, v90, v88
	v_mul_f32_e32 v90, v89, v88
	v_fma_f32 v91, -v87, v90, v89
	v_fmac_f32_e32 v90, v91, v88
	v_fma_f32 v87, -v87, v90, v89
	v_div_fmas_f32 v87, v87, v88, v90
	v_div_fixup_f32 v86, v87, v86, 1.0
	v_pk_mul_f32 v[78:79], v[78:79], v[86:87] op_sel_hi:[1,0]
	v_pk_mul_f32 v[76:77], v[76:77], v[86:87] op_sel_hi:[1,0]
	v_pk_mul_f32 v[74:75], v[74:75], v[86:87] op_sel_hi:[1,0]
	v_pk_mul_f32 v[72:73], v[72:73], v[86:87] op_sel_hi:[1,0]
	v_pk_mul_f32 v[70:71], v[70:71], v[86:87] op_sel_hi:[1,0]
	v_pk_mul_f32 v[68:69], v[68:69], v[86:87] op_sel_hi:[1,0]
	v_pk_mul_f32 v[88:89], v[66:67], v[86:87] op_sel_hi:[1,0]
	v_pk_mul_f32 v[86:87], v[64:65], v[86:87] op_sel_hi:[1,0]
	v_cvt_pk_bf16_f32 v64, v76, v77
	v_cvt_pk_bf16_f32 v65, v78, v79
	v_cvt_pk_bf16_f32 v66, v72, v73
	v_cvt_pk_bf16_f32 v67, v74, v75
	flat_store_dwordx4 v[82:83], v[64:67]
	s_nop 1
	v_cvt_pk_bf16_f32 v64, v68, v69
	v_cvt_pk_bf16_f32 v65, v70, v71
	v_cvt_pk_bf16_f32 v66, v86, v87
	v_cvt_pk_bf16_f32 v67, v88, v89
	flat_store_dwordx4 v[82:83], v[64:67] offset:256
	s_nop 0
	s_nop 0
	s_nop 0
	s_waitcnt vmcnt(14) lgkmcnt(0)
	v_mov_b32_e32 v64, v210
	v_mov_b32_e32 v65, v211
	v_mov_b32_e32 v66, v212
	v_mov_b32_e32 v67, v213
	v_mov_b32_e32 v68, v214
	v_mov_b32_e32 v69, v215
	v_mov_b32_e32 v70, v216
	v_mov_b32_e32 v71, v217
	v_mov_b32_e32 v72, v64
	v_mov_b32_e32 v73, v68
	v_mov_b32_e32 v68, v65
	v_mov_b32_e32 v64, v66
	v_mov_b32_e32 v65, v70
	v_mov_b32_e32 v70, v67
	v_pk_add_f32 v[66:67], v[72:73], v[68:69]
	v_pk_add_f32 v[64:65], v[64:65], v[70:71]
	s_nop 0
	v_pk_add_f32 v[64:65], v[66:67], v[64:65]
	v_lshlrev_b64 v[66:67], 10, v[80:81]
	v_add_f32_e32 v64, v64, v65
	ds_bpermute_b32 v65, v148, v64
	v_lshl_add_u64 v[66:67], s[6:7], 0, v[66:67]
	v_lshl_add_u64 v[66:67], v[66:67], 0, v[140:141]
	s_waitcnt lgkmcnt(0)
	v_add_f32_e32 v68, v64, v65
	ds_bpermute_b32 v69, v149, v68
	v_add_u32_e32 v64, 0x90, v142
	v_ashrrev_i32_e32 v65, 31, v64
	s_waitcnt lgkmcnt(0)
	v_add_f32_e32 v68, v68, v69
	v_fmamk_f32 v68, v68, 0x3a000000, v195
	v_mul_f32_e32 v69, 0x4f800000, v68
	v_cmp_gt_f32_e32 vcc, s48, v68
	s_nop 1
	v_cndmask_b32_e32 v70, v68, v69, vcc
	v_sqrt_f32_e32 v71, v70
	v_lshlrev_b64 v[68:69], 7, v[64:65]
	v_lshl_add_u64 v[68:69], v[134:135], 0, v[68:69]
	v_add_u32_e32 v72, -1, v71
	v_add_u32_e32 v73, 1, v71
	v_fma_f32 v74, -v72, v71, v70
	v_fma_f32 v75, -v73, v71, v70
	v_cmp_ge_f32_e64 s[0:1], 0, v74
	s_nop 1
	v_cndmask_b32_e64 v71, v71, v72, s[0:1]
	v_cmp_lt_f32_e64 s[0:1], 0, v75
	s_nop 1
	v_cndmask_b32_e64 v71, v71, v73, s[0:1]
	v_mul_f32_e32 v72, 0x37800000, v71
	v_cndmask_b32_e32 v71, v71, v72, vcc
	v_cmp_class_f32_e32 vcc, v70, v197
	s_nop 1
	v_cndmask_b32_e32 v70, v71, v70, vcc
	v_div_scale_f32 v71, s[0:1], v70, v70, 1.0
	v_rcp_f32_e32 v72, v71
	v_div_scale_f32 v73, vcc, 1.0, v70, 1.0
	v_fma_f32 v74, -v71, v72, 1.0
	v_fmac_f32_e32 v72, v74, v72
	v_mul_f32_e32 v74, v73, v72
	v_fma_f32 v75, -v71, v74, v73
	v_fmac_f32_e32 v74, v75, v72
	v_fma_f32 v71, -v71, v74, v73
	v_div_fmas_f32 v71, v71, v72, v74
	v_div_fixup_f32 v70, v71, v70, 1.0
	v_pk_mul_f32 v[62:63], v[62:63], v[70:71] op_sel_hi:[1,0]
	v_pk_mul_f32 v[60:61], v[60:61], v[70:71] op_sel_hi:[1,0]
	v_pk_mul_f32 v[58:59], v[58:59], v[70:71] op_sel_hi:[1,0]
	v_pk_mul_f32 v[56:57], v[56:57], v[70:71] op_sel_hi:[1,0]
	v_pk_mul_f32 v[54:55], v[54:55], v[70:71] op_sel_hi:[1,0]
	v_pk_mul_f32 v[52:53], v[52:53], v[70:71] op_sel_hi:[1,0]
	v_pk_mul_f32 v[72:73], v[50:51], v[70:71] op_sel_hi:[1,0]
	v_pk_mul_f32 v[70:71], v[48:49], v[70:71] op_sel_hi:[1,0]
	v_cvt_pk_bf16_f32 v48, v60, v61
	v_cvt_pk_bf16_f32 v49, v62, v63
	v_cvt_pk_bf16_f32 v50, v56, v57
	v_cvt_pk_bf16_f32 v51, v58, v59
	flat_store_dwordx4 v[66:67], v[48:51]
	s_nop 1
	v_cvt_pk_bf16_f32 v48, v52, v53
	v_cvt_pk_bf16_f32 v49, v54, v55
	v_cvt_pk_bf16_f32 v50, v70, v71
	v_cvt_pk_bf16_f32 v51, v72, v73
	flat_store_dwordx4 v[66:67], v[48:51] offset:256
	s_nop 0
	s_nop 0
	s_nop 0
	s_waitcnt vmcnt(14) lgkmcnt(0)
	v_mov_b32_e32 v48, v218
	v_mov_b32_e32 v49, v219
	v_mov_b32_e32 v50, v220
	v_mov_b32_e32 v51, v221
	v_mov_b32_e32 v52, v222
	v_mov_b32_e32 v53, v223
	v_mov_b32_e32 v54, v224
	v_mov_b32_e32 v55, v225
	v_mov_b32_e32 v56, v48
	v_mov_b32_e32 v57, v52
	v_mov_b32_e32 v52, v49
	v_mov_b32_e32 v48, v50
	v_mov_b32_e32 v49, v54
	v_mov_b32_e32 v54, v51
	v_pk_add_f32 v[50:51], v[56:57], v[52:53]
	v_pk_add_f32 v[48:49], v[48:49], v[54:55]
	s_nop 0
	v_pk_add_f32 v[48:49], v[50:51], v[48:49]
	v_lshlrev_b64 v[50:51], 10, v[64:65]
	v_add_f32_e32 v48, v48, v49
	ds_bpermute_b32 v49, v148, v48
	v_lshl_add_u64 v[50:51], s[6:7], 0, v[50:51]
	v_lshl_add_u64 v[50:51], v[50:51], 0, v[140:141]
	s_waitcnt lgkmcnt(0)
	v_add_f32_e32 v52, v48, v49
	ds_bpermute_b32 v53, v149, v52
	v_add_u32_e32 v48, 0xa0, v142
	v_ashrrev_i32_e32 v49, 31, v48
	s_waitcnt lgkmcnt(0)
	v_add_f32_e32 v52, v52, v53
	v_fmamk_f32 v52, v52, 0x3a000000, v195
	v_mul_f32_e32 v53, 0x4f800000, v52
	v_cmp_gt_f32_e32 vcc, s48, v52
	s_nop 1
	v_cndmask_b32_e32 v54, v52, v53, vcc
	v_sqrt_f32_e32 v55, v54
	v_lshlrev_b64 v[52:53], 7, v[48:49]
	v_lshl_add_u64 v[52:53], v[134:135], 0, v[52:53]
	v_add_u32_e32 v56, -1, v55
	v_add_u32_e32 v57, 1, v55
	v_fma_f32 v58, -v56, v55, v54
	v_fma_f32 v59, -v57, v55, v54
	v_cmp_ge_f32_e64 s[0:1], 0, v58
	s_nop 1
	v_cndmask_b32_e64 v55, v55, v56, s[0:1]
	v_cmp_lt_f32_e64 s[0:1], 0, v59
	s_nop 1
	v_cndmask_b32_e64 v55, v55, v57, s[0:1]
	v_mul_f32_e32 v56, 0x37800000, v55
	v_cndmask_b32_e32 v55, v55, v56, vcc
	v_cmp_class_f32_e32 vcc, v54, v197
	s_nop 1
	v_cndmask_b32_e32 v54, v55, v54, vcc
	v_div_scale_f32 v55, s[0:1], v54, v54, 1.0
	v_rcp_f32_e32 v56, v55
	v_div_scale_f32 v57, vcc, 1.0, v54, 1.0
	v_fma_f32 v58, -v55, v56, 1.0
	v_fmac_f32_e32 v56, v58, v56
	v_mul_f32_e32 v58, v57, v56
	v_fma_f32 v59, -v55, v58, v57
	v_fmac_f32_e32 v58, v59, v56
	v_fma_f32 v55, -v55, v58, v57
	v_div_fmas_f32 v55, v55, v56, v58
	v_div_fixup_f32 v54, v55, v54, 1.0
	v_pk_mul_f32 v[46:47], v[46:47], v[54:55] op_sel_hi:[1,0]
	v_pk_mul_f32 v[44:45], v[44:45], v[54:55] op_sel_hi:[1,0]
	v_pk_mul_f32 v[42:43], v[42:43], v[54:55] op_sel_hi:[1,0]
	v_pk_mul_f32 v[40:41], v[40:41], v[54:55] op_sel_hi:[1,0]
	v_pk_mul_f32 v[38:39], v[38:39], v[54:55] op_sel_hi:[1,0]
	v_pk_mul_f32 v[36:37], v[36:37], v[54:55] op_sel_hi:[1,0]
	v_pk_mul_f32 v[56:57], v[34:35], v[54:55] op_sel_hi:[1,0]
	v_pk_mul_f32 v[54:55], v[32:33], v[54:55] op_sel_hi:[1,0]
	v_cvt_pk_bf16_f32 v32, v44, v45
	v_cvt_pk_bf16_f32 v33, v46, v47
	v_cvt_pk_bf16_f32 v34, v40, v41
	v_cvt_pk_bf16_f32 v35, v42, v43
	flat_store_dwordx4 v[50:51], v[32:35]
	s_nop 1
	v_cvt_pk_bf16_f32 v32, v36, v37
	v_cvt_pk_bf16_f32 v33, v38, v39
	v_cvt_pk_bf16_f32 v34, v54, v55
	v_cvt_pk_bf16_f32 v35, v56, v57
	flat_store_dwordx4 v[50:51], v[32:35] offset:256
	s_nop 0
	s_nop 0
	s_nop 0
	s_waitcnt vmcnt(14) lgkmcnt(0)
	v_mov_b32_e32 v32, v226
	v_mov_b32_e32 v33, v227
	v_mov_b32_e32 v34, v228
	v_mov_b32_e32 v35, v229
	v_mov_b32_e32 v36, v230
	v_mov_b32_e32 v37, v231
	v_mov_b32_e32 v38, v232
	v_mov_b32_e32 v39, v233
	v_mov_b32_e32 v40, v32
	v_mov_b32_e32 v41, v36
	v_mov_b32_e32 v36, v33
	v_mov_b32_e32 v32, v34
	v_mov_b32_e32 v33, v38
	v_mov_b32_e32 v38, v35
	v_pk_add_f32 v[34:35], v[40:41], v[36:37]
	v_pk_add_f32 v[32:33], v[32:33], v[38:39]
	s_nop 0
	v_pk_add_f32 v[32:33], v[34:35], v[32:33]
	v_lshlrev_b64 v[34:35], 10, v[48:49]
	v_add_f32_e32 v32, v32, v33
	ds_bpermute_b32 v33, v148, v32
	v_lshl_add_u64 v[34:35], s[6:7], 0, v[34:35]
	v_lshl_add_u64 v[34:35], v[34:35], 0, v[140:141]
	s_waitcnt lgkmcnt(0)
	v_add_f32_e32 v36, v32, v33
	ds_bpermute_b32 v37, v149, v36
	v_add_u32_e32 v32, 0xb0, v142
	v_ashrrev_i32_e32 v33, 31, v32
	s_waitcnt lgkmcnt(0)
	v_add_f32_e32 v36, v36, v37
	v_fmamk_f32 v36, v36, 0x3a000000, v195
	v_mul_f32_e32 v37, 0x4f800000, v36
	v_cmp_gt_f32_e32 vcc, s48, v36
	s_nop 1
	v_cndmask_b32_e32 v38, v36, v37, vcc
	v_sqrt_f32_e32 v39, v38
	v_lshlrev_b64 v[36:37], 7, v[32:33]
	v_lshl_add_u64 v[36:37], v[134:135], 0, v[36:37]
	v_add_u32_e32 v40, -1, v39
	v_add_u32_e32 v41, 1, v39
	v_fma_f32 v42, -v40, v39, v38
	v_fma_f32 v43, -v41, v39, v38
	v_cmp_ge_f32_e64 s[0:1], 0, v42
	s_nop 1
	v_cndmask_b32_e64 v39, v39, v40, s[0:1]
	v_cmp_lt_f32_e64 s[0:1], 0, v43
	s_nop 1
	v_cndmask_b32_e64 v39, v39, v41, s[0:1]
	v_mul_f32_e32 v40, 0x37800000, v39
	v_cndmask_b32_e32 v39, v39, v40, vcc
	v_cmp_class_f32_e32 vcc, v38, v197
	s_nop 1
	v_cndmask_b32_e32 v38, v39, v38, vcc
	v_div_scale_f32 v39, s[0:1], v38, v38, 1.0
	v_rcp_f32_e32 v40, v39
	v_div_scale_f32 v41, vcc, 1.0, v38, 1.0
	v_fma_f32 v42, -v39, v40, 1.0
	v_fmac_f32_e32 v40, v42, v40
	v_mul_f32_e32 v42, v41, v40
	v_fma_f32 v43, -v39, v42, v41
	v_fmac_f32_e32 v42, v43, v40
	v_fma_f32 v39, -v39, v42, v41
	v_div_fmas_f32 v39, v39, v40, v42
	v_div_fixup_f32 v38, v39, v38, 1.0
	v_pk_mul_f32 v[30:31], v[30:31], v[38:39] op_sel_hi:[1,0]
	v_pk_mul_f32 v[28:29], v[28:29], v[38:39] op_sel_hi:[1,0]
	v_pk_mul_f32 v[26:27], v[26:27], v[38:39] op_sel_hi:[1,0]
	v_pk_mul_f32 v[24:25], v[24:25], v[38:39] op_sel_hi:[1,0]
	v_pk_mul_f32 v[22:23], v[22:23], v[38:39] op_sel_hi:[1,0]
	v_pk_mul_f32 v[20:21], v[20:21], v[38:39] op_sel_hi:[1,0]
	v_pk_mul_f32 v[40:41], v[18:19], v[38:39] op_sel_hi:[1,0]
	v_pk_mul_f32 v[38:39], v[16:17], v[38:39] op_sel_hi:[1,0]
	v_cvt_pk_bf16_f32 v16, v28, v29
	v_cvt_pk_bf16_f32 v17, v30, v31
	v_cvt_pk_bf16_f32 v18, v24, v25
	v_cvt_pk_bf16_f32 v19, v26, v27
	flat_store_dwordx4 v[34:35], v[16:19]
	s_nop 1
	v_cvt_pk_bf16_f32 v16, v20, v21
	v_cvt_pk_bf16_f32 v17, v22, v23
	v_cvt_pk_bf16_f32 v18, v38, v39
	v_cvt_pk_bf16_f32 v19, v40, v41
	flat_store_dwordx4 v[34:35], v[16:19] offset:256
	s_nop 0
	s_nop 0
	s_nop 0
	s_waitcnt vmcnt(14) lgkmcnt(0)
	v_mov_b32_e32 v16, v240
	v_mov_b32_e32 v17, v241
	v_mov_b32_e32 v18, v242
	v_mov_b32_e32 v19, v243
	v_mov_b32_e32 v20, v244
	v_mov_b32_e32 v21, v245
	v_mov_b32_e32 v22, v246
	v_mov_b32_e32 v23, v247
	v_mov_b32_e32 v24, v16
	v_mov_b32_e32 v25, v20
	v_mov_b32_e32 v20, v17
	v_mov_b32_e32 v16, v18
	v_mov_b32_e32 v17, v22
	v_mov_b32_e32 v22, v19
	v_pk_add_f32 v[18:19], v[24:25], v[20:21]
	v_pk_add_f32 v[16:17], v[16:17], v[22:23]
	s_nop 0
	v_pk_add_f32 v[16:17], v[18:19], v[16:17]
	s_nop 0
	v_add_f32_e32 v16, v16, v17
	ds_bpermute_b32 v17, v148, v16
	s_waitcnt lgkmcnt(0)
	v_add_f32_e32 v16, v16, v17
	ds_bpermute_b32 v17, v149, v16
	s_waitcnt lgkmcnt(0)
	v_add_f32_e32 v16, v16, v17
	v_fmamk_f32 v16, v16, 0x3a000000, v195
	v_mul_f32_e32 v17, 0x4f800000, v16
	v_cmp_gt_f32_e32 vcc, s48, v16
	s_nop 1
	v_cndmask_b32_e32 v18, v16, v17, vcc
	v_sqrt_f32_e32 v19, v18
	v_lshlrev_b64 v[16:17], 10, v[32:33]
	v_lshl_add_u64 v[16:17], s[6:7], 0, v[16:17]
	v_lshl_add_u64 v[16:17], v[16:17], 0, v[140:141]
	v_add_u32_e32 v20, -1, v19
	v_add_u32_e32 v21, 1, v19
	v_fma_f32 v22, -v20, v19, v18
	v_fma_f32 v23, -v21, v19, v18
	v_cmp_ge_f32_e64 s[0:1], 0, v22
	s_nop 1
	v_cndmask_b32_e64 v19, v19, v20, s[0:1]
	v_cmp_lt_f32_e64 s[0:1], 0, v23
	s_nop 1
	v_cndmask_b32_e64 v19, v19, v21, s[0:1]
	v_mul_f32_e32 v20, 0x37800000, v19
	v_cndmask_b32_e32 v19, v19, v20, vcc
	v_cmp_class_f32_e32 vcc, v18, v197
	s_nop 1
	v_cndmask_b32_e32 v18, v19, v18, vcc
	v_div_scale_f32 v19, s[0:1], v18, v18, 1.0
	v_rcp_f32_e32 v20, v19
	v_div_scale_f32 v21, vcc, 1.0, v18, 1.0
	s_mov_b64 s[0:1], -1
	v_fma_f32 v22, -v19, v20, 1.0
	v_fmac_f32_e32 v20, v22, v20
	v_mul_f32_e32 v22, v21, v20
	v_fma_f32 v23, -v19, v22, v21
	v_fmac_f32_e32 v22, v23, v20
	v_fma_f32 v19, -v19, v22, v21
	v_div_fmas_f32 v19, v19, v20, v22
	v_div_fixup_f32 v18, v19, v18, 1.0
	s_andn2_b64 vcc, exec, s[10:11]
	v_pk_mul_f32 v[14:15], v[14:15], v[18:19] op_sel_hi:[1,0]
	v_pk_mul_f32 v[12:13], v[12:13], v[18:19] op_sel_hi:[1,0]
	v_pk_mul_f32 v[10:11], v[10:11], v[18:19] op_sel_hi:[1,0]
	v_pk_mul_f32 v[8:9], v[8:9], v[18:19] op_sel_hi:[1,0]
	v_pk_mul_f32 v[6:7], v[6:7], v[18:19] op_sel_hi:[1,0]
	v_pk_mul_f32 v[4:5], v[4:5], v[18:19] op_sel_hi:[1,0]
	v_pk_mul_f32 v[20:21], v[2:3], v[18:19] op_sel_hi:[1,0]
	v_pk_mul_f32 v[18:19], v[0:1], v[18:19] op_sel_hi:[1,0]
	v_cvt_pk_bf16_f32 v0, v12, v13
	v_cvt_pk_bf16_f32 v1, v14, v15
	v_cvt_pk_bf16_f32 v2, v8, v9
	v_cvt_pk_bf16_f32 v3, v10, v11
	flat_store_dwordx4 v[16:17], v[0:3]
	s_nop 1
	v_cvt_pk_bf16_f32 v0, v4, v5
	v_cvt_pk_bf16_f32 v1, v6, v7
	v_cvt_pk_bf16_f32 v2, v18, v19
	v_cvt_pk_bf16_f32 v3, v20, v21
	flat_store_dwordx4 v[16:17], v[0:3] offset:256
	s_cbranch_vccnz .LBB0_168
	s_andn2_b64 vcc, exec, s[4:5]
	s_cbranch_vccnz .LBB0_167
	s_barrier
	s_branch .LBB0_167

.LBB0_544:
	s_or_b64 exec, exec, s[66:67]
	s_lshl_b64 s[66:67], s[46:47], 6
	v_lshl_add_u64 v[0:1], s[66:67], 0, v[20:21]
	v_mov_b64_e32 v[4:5], s[54:55]
	s_and_b32 s82, s64, 3
	v_mad_u64_u32 v[2:3], s[46:47], v0, s33, v[4:5]
	v_mad_i32_i24 v3, v1, s33, v3
	s_lshl_b32 s38, s82, 10
	v_lshl_add_u64 v[0:1], v[2:3], 0, s[38:39]
	v_mov_b32_e32 v95, v161
	v_lshl_add_u64 v[0:1], v[0:1], 0, v[94:95]
	s_movk_i32 s12, 0x1000
	v_add_co_u32_e32 v0, vcc, s12, v0
	s_ashr_i32 s65, s64, 31
	s_nop 0
	v_addc_co_u32_e32 v1, vcc, 0, v1, vcc
	global_load_dwordx4 v[200:203], v[0:1], off
	s_mov_b32 s83, s81
	s_nop 0
	s_nop 0
	v_lshl_add_u64 v[0:1], s[66:67], 0, v[22:23]
	v_mad_u64_u32 v[2:3], s[46:47], v0, s33, v[4:5]
	v_mad_i32_i24 v3, v1, s33, v3
	v_lshl_add_u64 v[0:1], v[2:3], 0, s[38:39]
	v_lshl_add_u64 v[0:1], v[0:1], 0, v[94:95]
	v_add_co_u32_e32 v0, vcc, s12, v0
	s_nop 1
	v_addc_co_u32_e32 v1, vcc, 0, v1, vcc
	global_load_dwordx4 v[204:207], v[0:1], off
	s_nop 0
	s_nop 0
	v_lshl_add_u64 v[0:1], s[66:67], 0, v[24:25]
	v_mad_u64_u32 v[2:3], s[46:47], v0, s33, v[4:5]
	v_mad_i32_i24 v3, v1, s33, v3
	v_lshl_add_u64 v[0:1], v[2:3], 0, s[38:39]
	v_lshl_add_u64 v[0:1], v[0:1], 0, v[94:95]
	v_add_co_u32_e32 v0, vcc, s12, v0
	s_nop 1
	v_addc_co_u32_e32 v1, vcc, 0, v1, vcc
	global_load_dwordx4 v[208:211], v[0:1], off
	s_nop 0
	s_nop 0
	v_lshl_add_u64 v[0:1], s[66:67], 0, v[26:27]
	v_mad_u64_u32 v[2:3], s[46:47], v0, s33, v[4:5]
	v_mad_i32_i24 v3, v1, s33, v3
	v_lshl_add_u64 v[0:1], v[2:3], 0, s[38:39]
	v_lshl_add_u64 v[0:1], v[0:1], 0, v[94:95]
	v_add_co_u32_e32 v0, vcc, s12, v0
	s_nop 1
	v_addc_co_u32_e32 v1, vcc, 0, v1, vcc
	global_load_dwordx4 v[212:215], v[0:1], off
	s_nop 0
	s_nop 0
	v_lshl_add_u64 v[0:1], s[66:67], 0, v[28:29]
	v_mad_u64_u32 v[2:3], s[46:47], v0, s33, v[4:5]
	v_mad_i32_i24 v3, v1, s33, v3
	v_lshl_add_u64 v[0:1], v[2:3], 0, s[38:39]
	v_lshl_add_u64 v[0:1], v[0:1], 0, v[94:95]
	v_add_co_u32_e32 v0, vcc, s12, v0
	s_nop 1
	v_addc_co_u32_e32 v1, vcc, 0, v1, vcc
	global_load_dwordx4 v[216:219], v[0:1], off
	s_nop 0
	s_nop 0
	v_lshl_add_u64 v[0:1], s[66:67], 0, v[30:31]
	v_mad_u64_u32 v[2:3], s[46:47], v0, s33, v[4:5]
	v_mad_i32_i24 v3, v1, s33, v3
	v_lshl_add_u64 v[0:1], v[2:3], 0, s[38:39]
	v_lshl_add_u64 v[0:1], v[0:1], 0, v[94:95]
	v_add_co_u32_e32 v0, vcc, s12, v0
	s_nop 1
	v_addc_co_u32_e32 v1, vcc, 0, v1, vcc
	global_load_dwordx4 v[220:223], v[0:1], off
	s_nop 0
	s_nop 0
	v_lshl_add_u64 v[0:1], s[66:67], 0, v[32:33]
	v_mad_u64_u32 v[2:3], s[46:47], v0, s33, v[4:5]
	v_mad_i32_i24 v3, v1, s33, v3
	v_lshl_add_u64 v[0:1], v[2:3], 0, s[38:39]
	v_lshl_add_u64 v[0:1], v[0:1], 0, v[94:95]
	v_add_co_u32_e32 v0, vcc, s12, v0
	s_nop 1
	v_addc_co_u32_e32 v1, vcc, 0, v1, vcc
	global_load_dwordx4 v[224:227], v[0:1], off
	s_nop 0
	s_nop 0
	v_lshl_add_u64 v[0:1], s[66:67], 0, v[34:35]
	v_mad_u64_u32 v[2:3], s[46:47], v0, s33, v[4:5]
	v_mad_i32_i24 v3, v1, s33, v3
	v_lshl_add_u64 v[0:1], v[2:3], 0, s[38:39]
	v_lshl_add_u64 v[0:1], v[0:1], 0, v[94:95]
	v_add_co_u32_e32 v0, vcc, s12, v0
	s_lshl_b64 s[46:47], s[64:65], 16
	s_nop 0
	v_addc_co_u32_e32 v1, vcc, 0, v1, vcc
	global_load_dwordx4 v[228:231], v[0:1], off
	s_add_u32 s46, s78, s46
	s_addc_u32 s47, s79, s47
	s_lshl_b32 s38, s82, 8
	v_readlane_b32 s12, v253, 25
	v_readlane_b32 s26, v253, 39
	v_readlane_b32 s27, v253, 40
	s_movk_i32 s12, 0x2000
	s_mov_b32 s82, 32
	v_readlane_b32 s13, v253, 26
	v_readlane_b32 s14, v253, 27
	v_readlane_b32 s15, v253, 28
	v_readlane_b32 s16, v253, 29
	v_readlane_b32 s17, v253, 30
	v_readlane_b32 s18, v253, 31
	v_readlane_b32 s19, v253, 32
	v_readlane_b32 s20, v253, 33
	v_readlane_b32 s21, v253, 34
	v_readlane_b32 s22, v253, 35
	v_readlane_b32 s23, v253, 36
	v_readlane_b32 s24, v253, 37
	v_readlane_b32 s25, v253, 38
	s_waitcnt vmcnt(0) lgkmcnt(0)
	ds_write_b128 v102, v[200:203]
	ds_write_b128 v102, v[204:207] offset:8192
	ds_write_b128 v102, v[208:211] offset:16384
	ds_write_b128 v102, v[212:215] offset:24576
	ds_write_b128 v102, v[216:219] offset:32768
	ds_write_b128 v102, v[220:223] offset:40960
	ds_write_b128 v102, v[224:227] offset:49152
	ds_write_b128 v102, v[228:231] offset:57344
	s_waitcnt lgkmcnt(0)
	s_barrier
	ds_read_u16 v0, v122
	ds_read_u16 v1, v122 offset:1024
	s_waitcnt lgkmcnt(0)
	v_lshl_or_b32 v0, v1, 16, v0
	ds_read_u16 v1, v122 offset:2048
	ds_read_u16 v2, v122 offset:3072
	s_waitcnt lgkmcnt(0)
	v_lshl_or_b32 v1, v2, 16, v1
	ds_read_u16 v2, v122 offset:4096
	ds_read_u16 v3, v122 offset:5120
	s_waitcnt lgkmcnt(0)
	v_lshl_or_b32 v2, v3, 16, v2
	ds_read_u16 v3, v122 offset:6144
	ds_read_u16 v4, v122 offset:7168
	s_waitcnt lgkmcnt(0)
	v_lshl_or_b32 v3, v4, 16, v3
	v_lshl_add_u64 v[4:5], v[36:37], 1, s[46:47]
	flat_store_dwordx4 v[4:5], v[0:3]
	ds_read_u16 v0, v123
	ds_read_u16 v1, v123 offset:1024
	s_waitcnt lgkmcnt(0)
	v_lshl_or_b32 v0, v1, 16, v0
	ds_read_u16 v1, v123 offset:2048
	ds_read_u16 v2, v123 offset:3072
	s_waitcnt lgkmcnt(0)
	v_lshl_or_b32 v1, v2, 16, v1
	ds_read_u16 v2, v123 offset:4096
	ds_read_u16 v3, v123 offset:5120
	s_waitcnt lgkmcnt(0)
	v_lshl_or_b32 v2, v3, 16, v2
	ds_read_u16 v3, v123 offset:6144
	ds_read_u16 v4, v123 offset:7168
	s_waitcnt lgkmcnt(0)
	v_lshl_or_b32 v3, v4, 16, v3
	v_lshl_add_u64 v[4:5], v[38:39], 1, s[46:47]
	flat_store_dwordx4 v[4:5], v[0:3]
	ds_read_u16 v0, v124
	ds_read_u16 v1, v124 offset:1024
	s_waitcnt lgkmcnt(0)
	v_lshl_or_b32 v0, v1, 16, v0
	ds_read_u16 v1, v124 offset:2048
	ds_read_u16 v2, v124 offset:3072
	s_waitcnt lgkmcnt(0)
	v_lshl_or_b32 v1, v2, 16, v1
	ds_read_u16 v2, v124 offset:4096
	ds_read_u16 v3, v124 offset:5120
	s_waitcnt lgkmcnt(0)
	v_lshl_or_b32 v2, v3, 16, v2
	ds_read_u16 v3, v124 offset:6144
	ds_read_u16 v4, v124 offset:7168
	s_waitcnt lgkmcnt(0)
	v_lshl_or_b32 v3, v4, 16, v3
	v_lshl_add_u64 v[4:5], v[40:41], 1, s[46:47]
	flat_store_dwordx4 v[4:5], v[0:3]
	ds_read_u16 v0, v125
	ds_read_u16 v1, v125 offset:1024
	s_waitcnt lgkmcnt(0)
	v_lshl_or_b32 v0, v1, 16, v0
	ds_read_u16 v1, v125 offset:2048
	ds_read_u16 v2, v125 offset:3072
	s_waitcnt lgkmcnt(0)
	v_lshl_or_b32 v1, v2, 16, v1
	ds_read_u16 v2, v125 offset:4096
	ds_read_u16 v3, v125 offset:5120
	s_waitcnt lgkmcnt(0)
	v_lshl_or_b32 v2, v3, 16, v2
	ds_read_u16 v3, v125 offset:6144
	ds_read_u16 v4, v125 offset:7168
	s_waitcnt lgkmcnt(0)
	v_lshl_or_b32 v3, v4, 16, v3
	v_lshl_add_u64 v[4:5], v[42:43], 1, s[46:47]
	flat_store_dwordx4 v[4:5], v[0:3]
	ds_read_u16 v0, v126
	ds_read_u16 v1, v126 offset:1024
	s_waitcnt lgkmcnt(0)
	v_lshl_or_b32 v0, v1, 16, v0
	ds_read_u16 v1, v126 offset:2048
	ds_read_u16 v2, v126 offset:3072
	s_waitcnt lgkmcnt(0)
	v_lshl_or_b32 v1, v2, 16, v1
	ds_read_u16 v2, v126 offset:4096
	ds_read_u16 v3, v126 offset:5120
	s_waitcnt lgkmcnt(0)
	v_lshl_or_b32 v2, v3, 16, v2
	ds_read_u16 v3, v126 offset:6144
	ds_read_u16 v4, v126 offset:7168
	s_waitcnt lgkmcnt(0)
	v_lshl_or_b32 v3, v4, 16, v3
	v_lshl_add_u64 v[4:5], v[44:45], 1, s[46:47]
	flat_store_dwordx4 v[4:5], v[0:3]
	ds_read_u16 v0, v127
	ds_read_u16 v1, v127 offset:1024
	s_waitcnt lgkmcnt(0)
	v_lshl_or_b32 v0, v1, 16, v0
	ds_read_u16 v1, v127 offset:2048
	ds_read_u16 v2, v127 offset:3072
	s_waitcnt lgkmcnt(0)
	v_lshl_or_b32 v1, v2, 16, v1
	ds_read_u16 v2, v127 offset:4096
	ds_read_u16 v3, v127 offset:5120
	s_waitcnt lgkmcnt(0)
	v_lshl_or_b32 v2, v3, 16, v2
	ds_read_u16 v3, v127 offset:6144
	ds_read_u16 v4, v127 offset:7168
	s_waitcnt lgkmcnt(0)
	v_lshl_or_b32 v3, v4, 16, v3
	v_lshl_add_u64 v[4:5], v[46:47], 1, s[46:47]
	flat_store_dwordx4 v[4:5], v[0:3]
	ds_read_u16 v0, v128
	ds_read_u16 v1, v128 offset:1024
	s_waitcnt lgkmcnt(0)
	v_lshl_or_b32 v0, v1, 16, v0
	ds_read_u16 v1, v128 offset:2048
	ds_read_u16 v2, v128 offset:3072
	s_waitcnt lgkmcnt(0)
	v_lshl_or_b32 v1, v2, 16, v1
	ds_read_u16 v2, v128 offset:4096
	ds_read_u16 v3, v128 offset:5120
	s_waitcnt lgkmcnt(0)
	v_lshl_or_b32 v2, v3, 16, v2
	ds_read_u16 v3, v128 offset:6144
	ds_read_u16 v4, v128 offset:7168
	s_waitcnt lgkmcnt(0)
	v_lshl_or_b32 v3, v4, 16, v3
	v_lshl_add_u64 v[4:5], v[48:49], 1, s[46:47]
	flat_store_dwordx4 v[4:5], v[0:3]
	ds_read_u16 v0, v129
	ds_read_u16 v1, v129 offset:1024
	s_waitcnt lgkmcnt(0)
	v_lshl_or_b32 v0, v1, 16, v0
	ds_read_u16 v1, v129 offset:2048
	ds_read_u16 v2, v129 offset:3072
	s_waitcnt lgkmcnt(0)
	v_lshl_or_b32 v1, v2, 16, v1
	ds_read_u16 v2, v129 offset:4096
	ds_read_u16 v3, v129 offset:5120
	s_waitcnt lgkmcnt(0)
	v_lshl_or_b32 v2, v3, 16, v2
	ds_read_u16 v3, v129 offset:6144
	ds_read_u16 v4, v129 offset:7168
	s_waitcnt lgkmcnt(0)
	v_lshl_or_b32 v3, v4, 16, v3
	v_lshl_add_u64 v[4:5], v[50:51], 1, s[46:47]
	flat_store_dwordx4 v[4:5], v[0:3]
	s_waitcnt lgkmcnt(0)
	s_barrier
	v_or_b32_sdwa v2, s38, v16 dst_sel:DWORD dst_unused:UNUSED_PAD src0_sel:DWORD src1_sel:BYTE_0
	v_or_b32_e32 v0, s80, v2
	v_mov_b32_e32 v1, v161
	v_lshl_add_u64 v[0:1], v[0:1], 2, s[26:27]
	global_load_dword v95, v[0:1], off
	v_lshlrev_b32_e32 v0, 2, v2
	v_mov_b32_e32 v1, v161
	v_lshl_add_u64 v[96:97], s[58:59], 0, v[0:1]
	v_add_co_u32_e32 v4, vcc, s12, v96
	s_movk_i32 s12, 0x4000
	s_nop 0
	v_addc_co_u32_e32 v5, vcc, 0, v97, vcc
	v_add_co_u32_e32 v8, vcc, s12, v96
	s_movk_i32 s12, 0x6000
	s_nop 0
	v_addc_co_u32_e32 v9, vcc, 0, v97, vcc
	global_load_dword v0, v0, s[58:59]
	s_nop 0
	global_load_dword v2, v[4:5], off offset:-4096
	s_nop 0
	global_load_dword v4, v[4:5], off
	s_nop 0
	global_load_dword v6, v[8:9], off offset:-4096
	global_load_dword v1, v[8:9], off
	v_add_co_u32_e32 v8, vcc, s12, v96
	s_mov_b32 s12, 0x8000
	s_nop 0
	v_addc_co_u32_e32 v9, vcc, 0, v97, vcc
	global_load_dword v3, v[8:9], off offset:-4096
	global_load_dword v5, v[8:9], off
	v_add_co_u32_e32 v8, vcc, s12, v96
	s_mov_b32 s12, 0xa000
	s_nop 0
	v_addc_co_u32_e32 v9, vcc, 0, v97, vcc
	v_add_co_u32_e32 v12, vcc, s12, v96
	s_mov_b32 s12, 0xc000
	s_nop 0
	v_addc_co_u32_e32 v13, vcc, 0, v97, vcc
	v_add_co_u32_e32 v98, vcc, s12, v96
	global_load_dword v7, v[8:9], off offset:-4096
	s_nop 0
	global_load_dword v8, v[8:9], off
	v_addc_co_u32_e32 v99, vcc, 0, v97, vcc
	global_load_dword v10, v[12:13], off offset:-4096
	s_nop 0
	global_load_dword v12, v[12:13], off
	s_nop 0
	global_load_dword v14, v[98:99], off offset:-4096
	global_load_dword v9, v[98:99], off
	v_add_co_u32_e32 v98, vcc, s2, v96
	s_nop 1
	v_addc_co_u32_e32 v99, vcc, 0, v97, vcc
	v_add_co_u32_e32 v96, vcc, 0xf000, v96
	global_load_dword v11, v[98:99], off offset:-4096
	global_load_dword v13, v[98:99], off
	v_addc_co_u32_e32 v97, vcc, 0, v97, vcc
	global_load_dword v15, v[96:97], off
	v_mov_b32_e32 v96, 0
	v_mov_b32_e32 v97, v121

.LBB0_919:
	v_lshl_add_u32 v180, s28, 8, v206
	v_ashrrev_i32_e32 v181, 31, v180
	v_lshlrev_b64 v[184:185], 7, v[180:181]
	v_lshl_add_u64 v[132:133], v[172:173], 0, v[184:185]
	global_load_dwordx4 v[138:141], v[132:133], off
	global_load_dwordx4 v[142:145], v[132:133], off offset:16
	global_load_dwordx4 v[146:149], v[132:133], off offset:2048
	global_load_dwordx4 v[150:153], v[132:133], off offset:2064
	v_add_co_u32_e32 v248, vcc, 0x1000, v132
	s_nop 1
	v_addc_co_u32_e32 v249, vcc, 0, v133, vcc
	global_load_dwordx4 v[226:229], v[248:249], off
	global_load_dwordx4 v[230:233], v[248:249], off offset:16
	global_load_dwordx4 v[240:243], v[248:249], off offset:2048
	global_load_dwordx4 v[244:247], v[248:249], off offset:2064
	s_nop 0
	s_nop 0
	v_or_b32_e32 v198, 16, v180
	v_ashrrev_i32_e32 v199, 31, v198
	v_lshlrev_b64 v[186:187], 7, v[198:199]
	v_or_b32_e32 v200, 32, v180
	v_ashrrev_i32_e32 v201, 31, v200
	v_lshlrev_b64 v[188:189], 7, v[200:201]
	v_or_b32_e32 v202, 48, v180
	v_ashrrev_i32_e32 v203, 31, v202
	v_lshlrev_b64 v[190:191], 7, v[202:203]
	v_lshl_or_b32 v178, s26, 8, v211
	v_ashrrev_i32_e32 v179, 31, v178
	v_lshlrev_b64 v[218:219], 1, v[178:179]
	v_lshl_add_u64 v[182:183], s[12:13], 0, v[218:219]
	v_lshlrev_b64 v[220:221], 12, v[180:181]
	s_lshl_b32 s26, s26, 2
	s_ashr_i32 s27, s26, 31
	s_waitcnt vmcnt(6) lgkmcnt(0)
	v_mov_b32_e32 v128, v138
	v_mov_b32_e32 v129, v139
	v_mov_b32_e32 v130, v140
	v_mov_b32_e32 v131, v141
	v_mov_b32_e32 v132, v142
	v_mov_b32_e32 v133, v143
	v_mov_b32_e32 v134, v144
	v_mov_b32_e32 v135, v145
	v_mov_b32_e32 v136, v128
	v_mov_b32_e32 v137, v132
	v_mov_b32_e32 v132, v129
	v_pk_add_f32 v[128:129], v[136:137], v[132:133]
	v_mov_b32_e32 v132, v130
	v_mov_b32_e32 v133, v134
	v_mov_b32_e32 v134, v131
	v_pk_add_f32 v[130:131], v[132:133], v[134:135]
	s_nop 0
	v_pk_add_f32 v[128:129], v[128:129], v[130:131]
	v_and_b32_e32 v130, 64, v236
	v_add_f32_e32 v128, v128, v129
	v_xor_b32_e32 v129, 16, v236
	v_add_u32_e32 v130, 64, v130
	v_cmp_lt_i32_e32 vcc, v129, v130
	s_nop 1
	v_cndmask_b32_e32 v129, v236, v129, vcc
	v_lshlrev_b32_e32 v212, 2, v129
	ds_bpermute_b32 v129, v212, v128
	s_waitcnt lgkmcnt(0)
	v_add_f32_e32 v128, v128, v129
	v_xor_b32_e32 v129, 32, v236
	v_cmp_lt_i32_e32 vcc, v129, v130
	s_nop 1
	v_cndmask_b32_e32 v129, v236, v129, vcc
	v_lshlrev_b32_e32 v213, 2, v129
	ds_bpermute_b32 v129, v213, v128
	s_waitcnt lgkmcnt(0)
	v_add_f32_e32 v128, v128, v129
	v_fmamk_f32 v128, v128, 0x3a000000, v195
	v_div_scale_f32 v129, s[28:29], v128, v128, 1.0
	v_rcp_f32_e32 v130, v129
	s_nop 0
	v_fma_f32 v131, -v129, v130, 1.0
	v_fmac_f32_e32 v130, v131, v130
	v_div_scale_f32 v131, vcc, 1.0, v128, 1.0
	v_mul_f32_e32 v132, v131, v130
	v_fma_f32 v133, -v129, v132, v131
	v_fmac_f32_e32 v132, v133, v130
	v_fma_f32 v129, -v129, v132, v131
	v_div_fmas_f32 v129, v129, v130, v132
	v_lshl_add_u64 v[132:133], v[172:173], 0, v[186:187]
	v_div_fixup_f32 v192, v129, v128, 1.0
	s_nop 0
	s_nop 0
	s_nop 0
	s_waitcnt vmcnt(4) lgkmcnt(0)
	v_mov_b32_e32 v128, v146
	v_mov_b32_e32 v129, v147
	v_mov_b32_e32 v130, v148
	v_mov_b32_e32 v131, v149
	v_mov_b32_e32 v132, v150
	v_mov_b32_e32 v133, v151
	v_mov_b32_e32 v134, v152
	v_mov_b32_e32 v135, v153
	v_mov_b32_e32 v136, v128
	v_mov_b32_e32 v137, v132
	v_mov_b32_e32 v132, v129
	v_pk_add_f32 v[128:129], v[136:137], v[132:133]
	v_mov_b32_e32 v132, v130
	v_mov_b32_e32 v133, v134
	v_mov_b32_e32 v134, v131
	v_pk_add_f32 v[130:131], v[132:133], v[134:135]
	s_nop 0
	v_pk_add_f32 v[128:129], v[128:129], v[130:131]
	s_nop 0
	v_add_f32_e32 v128, v128, v129
	ds_bpermute_b32 v129, v212, v128
	s_waitcnt lgkmcnt(0)
	v_add_f32_e32 v128, v128, v129
	ds_bpermute_b32 v129, v213, v128
	s_waitcnt lgkmcnt(0)
	v_add_f32_e32 v128, v128, v129
	v_fmamk_f32 v128, v128, 0x3a000000, v195
	v_div_scale_f32 v129, s[28:29], v128, v128, 1.0
	v_rcp_f32_e32 v130, v129
	s_nop 0
	v_fma_f32 v131, -v129, v130, 1.0
	v_fmac_f32_e32 v130, v131, v130
	v_div_scale_f32 v131, vcc, 1.0, v128, 1.0
	v_mul_f32_e32 v132, v131, v130
	v_fma_f32 v133, -v129, v132, v131
	v_fmac_f32_e32 v132, v133, v130
	v_fma_f32 v129, -v129, v132, v131
	v_div_fmas_f32 v129, v129, v130, v132
	v_lshl_add_u64 v[132:133], v[172:173], 0, v[188:189]
	v_div_fixup_f32 v194, v129, v128, 1.0
	s_nop 0
	s_nop 0
	s_nop 0
	s_waitcnt vmcnt(2) lgkmcnt(0)
	v_mov_b32_e32 v128, v226
	v_mov_b32_e32 v129, v227
	v_mov_b32_e32 v130, v228
	v_mov_b32_e32 v131, v229
	v_mov_b32_e32 v132, v230
	v_mov_b32_e32 v133, v231
	v_mov_b32_e32 v134, v232
	v_mov_b32_e32 v135, v233
	v_mov_b32_e32 v136, v128
	v_mov_b32_e32 v137, v132
	v_mov_b32_e32 v132, v129
	v_pk_add_f32 v[128:129], v[136:137], v[132:133]
	v_mov_b32_e32 v132, v130
	v_mov_b32_e32 v133, v134
	v_mov_b32_e32 v134, v131
	v_pk_add_f32 v[130:131], v[132:133], v[134:135]
	s_nop 0
	v_pk_add_f32 v[128:129], v[128:129], v[130:131]
	s_nop 0
	v_add_f32_e32 v128, v128, v129
	ds_bpermute_b32 v129, v212, v128
	s_waitcnt lgkmcnt(0)
	v_add_f32_e32 v128, v128, v129
	ds_bpermute_b32 v129, v213, v128
	s_waitcnt lgkmcnt(0)
	v_add_f32_e32 v128, v128, v129
	v_fmamk_f32 v128, v128, 0x3a000000, v195
	v_div_scale_f32 v129, s[28:29], v128, v128, 1.0
	v_rcp_f32_e32 v130, v129
	s_nop 0
	v_fma_f32 v131, -v129, v130, 1.0
	v_fmac_f32_e32 v130, v131, v130
	v_div_scale_f32 v131, vcc, 1.0, v128, 1.0
	v_mul_f32_e32 v132, v131, v130
	v_fma_f32 v133, -v129, v132, v131
	v_fmac_f32_e32 v132, v133, v130
	v_fma_f32 v129, -v129, v132, v131
	v_div_fmas_f32 v129, v129, v130, v132
	v_div_fixup_f32 v196, v129, v128, 1.0
	v_lshl_add_u64 v[128:129], v[172:173], 0, v[190:191]
	s_nop 0
	s_nop 0
	s_nop 0
	s_waitcnt vmcnt(0) lgkmcnt(0)
	v_mov_b32_e32 v132, v240
	v_mov_b32_e32 v133, v241
	v_mov_b32_e32 v134, v242
	v_mov_b32_e32 v135, v243
	v_mov_b32_e32 v128, v244
	v_mov_b32_e32 v129, v245
	v_mov_b32_e32 v130, v246
	v_mov_b32_e32 v131, v247
	v_mov_b32_e32 v136, v132
	v_mov_b32_e32 v137, v128
	v_mov_b32_e32 v128, v133
	v_mov_b32_e32 v132, v134
	v_mov_b32_e32 v133, v130
	v_mov_b32_e32 v130, v135
	v_pk_add_f32 v[128:129], v[136:137], v[128:129]
	v_pk_add_f32 v[130:131], v[132:133], v[130:131]
	s_nop 0
	v_pk_add_f32 v[128:129], v[128:129], v[130:131]
	s_nop 0
	v_add_f32_e32 v128, v128, v129
	ds_bpermute_b32 v129, v212, v128
	s_waitcnt lgkmcnt(0)
	v_add_f32_e32 v128, v128, v129
	ds_bpermute_b32 v129, v213, v128
	s_waitcnt lgkmcnt(0)
	v_add_f32_e32 v128, v128, v129
	v_fmamk_f32 v128, v128, 0x3a000000, v195
	v_div_scale_f32 v129, s[28:29], v128, v128, 1.0
	v_rcp_f32_e32 v130, v129
	s_nop 0
	v_fma_f32 v131, -v129, v130, 1.0
	v_fmac_f32_e32 v130, v131, v130
	v_div_scale_f32 v131, vcc, 1.0, v128, 1.0
	v_mul_f32_e32 v132, v131, v130
	v_fma_f32 v133, -v129, v132, v131
	v_fmac_f32_e32 v132, v133, v130
	v_fma_f32 v129, -v129, v132, v131
	v_div_fmas_f32 v129, v129, v130, v132
	v_div_fixup_f32 v204, v129, v128, 1.0
	v_lshl_add_u64 v[128:129], v[182:183], 0, v[220:221]
	flat_load_dwordx4 v[214:217], v[128:129]
	flat_load_dwordx4 v[152:155], v[128:129] offset:256
	v_lshlrev_b64 v[128:129], 12, v[198:199]
	v_lshl_add_u64 v[128:129], v[182:183], 0, v[128:129]
	flat_load_dwordx4 v[148:151], v[128:129]
	flat_load_dwordx4 v[144:147], v[128:129] offset:256
	v_lshlrev_b64 v[128:129], 12, v[200:201]
	v_lshl_add_u64 v[128:129], v[182:183], 0, v[128:129]
	flat_load_dwordx4 v[140:143], v[128:129]
	flat_load_dwordx4 v[136:139], v[128:129] offset:256
	v_lshlrev_b64 v[128:129], 12, v[202:203]
	v_lshl_add_u64 v[128:129], v[182:183], 0, v[128:129]
	flat_load_dwordx4 v[132:135], v[128:129]
	s_nop 0
	flat_load_dwordx4 v[128:131], v[128:129] offset:256
	s_waitcnt vmcnt(0) lgkmcnt(0)
	v_lshlrev_b32_e32 v222, 16, v214
	v_and_b32_e32 v223, 0xffff0000, v214
	v_lshlrev_b32_e32 v214, 16, v215
	v_and_b32_e32 v215, 0xffff0000, v215
	v_lshlrev_b32_e32 v224, 16, v216
	v_and_b32_e32 v225, 0xffff0000, v216
	v_lshlrev_b32_e32 v216, 16, v217
	v_and_b32_e32 v217, 0xffff0000, v217
	v_pk_fma_f32 v[126:127], v[126:127], v[192:193], v[214:215] op_sel_hi:[1,0,1]
	v_pk_fma_f32 v[124:125], v[124:125], v[192:193], v[222:223] op_sel_hi:[1,0,1]
	v_pk_fma_f32 v[214:215], v[122:123], v[192:193], v[216:217] op_sel_hi:[1,0,1]
	v_pk_fma_f32 v[122:123], v[120:121], v[192:193], v[224:225] op_sel_hi:[1,0,1]
	v_mul_f32_e32 v120, v125, v125
	v_mul_f32_e32 v121, v127, v127
	v_fmac_f32_e32 v120, v124, v124
	v_fmac_f32_e32 v121, v126, v126
	v_add_f32_e32 v120, v120, v121
	v_mul_f32_e32 v121, v123, v123
	v_mul_f32_e32 v181, v215, v215
	v_fmac_f32_e32 v121, v122, v122
	v_fmac_f32_e32 v181, v214, v214
	v_add_f32_e32 v121, v121, v181
	v_add_f32_e32 v181, v120, v121
	v_cvt_pk_bf16_f32 v120, v124, v125
	v_lshl_add_u64 v[124:125], s[12:13], 0, v[220:221]
	v_cvt_pk_bf16_f32 v121, v126, v127
	v_cvt_pk_bf16_f32 v122, v122, v123
	v_cvt_pk_bf16_f32 v123, v214, v215
	v_lshl_add_u64 v[124:125], v[124:125], 0, v[218:219]
	flat_store_dwordx4 v[124:125], v[120:123]
	v_lshlrev_b32_e32 v126, 16, v154
	v_and_b32_e32 v127, 0xffff0000, v154
	v_lshlrev_b32_e32 v120, 16, v152
	v_and_b32_e32 v121, 0xffff0000, v152
	v_lshlrev_b32_e32 v122, 16, v153
	v_and_b32_e32 v123, 0xffff0000, v153
	v_lshlrev_b32_e32 v152, 16, v155
	v_and_b32_e32 v153, 0xffff0000, v155
	v_pk_fma_f32 v[118:119], v[118:119], v[192:193], v[122:123] op_sel_hi:[1,0,1]
	v_pk_fma_f32 v[116:117], v[116:117], v[192:193], v[120:121] op_sel_hi:[1,0,1]
	v_pk_fma_f32 v[120:121], v[114:115], v[192:193], v[152:153] op_sel_hi:[1,0,1]
	v_pk_fma_f32 v[114:115], v[112:113], v[192:193], v[126:127] op_sel_hi:[1,0,1]
	v_mul_f32_e32 v112, v117, v117
	v_mul_f32_e32 v113, v119, v119
	v_fmac_f32_e32 v112, v116, v116
	v_fmac_f32_e32 v113, v118, v118
	v_add_f32_e32 v112, v112, v113
	v_mul_f32_e32 v113, v115, v115
	v_mul_f32_e32 v122, v121, v121
	v_fmac_f32_e32 v113, v114, v114
	v_fmac_f32_e32 v122, v120, v120
	v_add_f32_e32 v113, v113, v122
	v_add_f32_e32 v112, v112, v113
	v_add_f32_e32 v122, v181, v112
	v_cvt_pk_bf16_f32 v112, v116, v117
	v_cvt_pk_bf16_f32 v113, v118, v119
	v_cvt_pk_bf16_f32 v114, v114, v115
	v_cvt_pk_bf16_f32 v115, v120, v121
	flat_store_dwordx4 v[124:125], v[112:115] offset:256
	ds_bpermute_b32 v112, v212, v122
	s_waitcnt lgkmcnt(0)
	v_add_f32_e32 v112, v122, v112
	ds_bpermute_b32 v113, v213, v112
	s_and_saveexec_b64 s[28:29], s[0:1]
	v_readlane_b32 s70, v255, 11
	v_readlane_b32 s71, v255, 12
	s_cbranch_execz .LBB0_921
	v_lshl_add_u64 v[114:115], s[14:15], 0, v[184:185]
	v_lshl_add_u64 v[114:115], s[26:27], 2, v[114:115]
	s_lshl_b32 s38, s61, 2
	v_lshl_add_u64 v[114:115], v[114:115], 0, s[38:39]
	s_waitcnt lgkmcnt(0)
	v_add_f32_e32 v112, v112, v113
	flat_store_dword v[114:115], v112

.LBB0_927:
	s_or_b64 exec, exec, s[28:29]
	v_add_u32_e32 v64, 0x80, v180
	s_waitcnt lgkmcnt(0)
	v_ashrrev_i32_e32 v65, 31, v64
	v_lshlrev_b64 v[88:89], 7, v[64:65]
	v_lshl_add_u64 v[70:71], v[172:173], 0, v[88:89]
	global_load_dwordx4 v[110:113], v[70:71], off
	global_load_dwordx4 v[114:117], v[70:71], off offset:16
	global_load_dwordx4 v[120:123], v[70:71], off offset:2048
	global_load_dwordx4 v[124:127], v[70:71], off offset:2064
	v_add_co_u32_e32 v248, vcc, 0x1000, v70
	s_nop 1
	v_addc_co_u32_e32 v249, vcc, 0, v71, vcc
	global_load_dwordx4 v[226:229], v[248:249], off
	global_load_dwordx4 v[230:233], v[248:249], off offset:16
	global_load_dwordx4 v[240:243], v[248:249], off offset:2048
	global_load_dwordx4 v[244:247], v[248:249], off offset:2064
	s_nop 0
	s_nop 0
	v_add_u32_e32 v100, 0x90, v180
	v_ashrrev_i32_e32 v101, 31, v100
	v_lshlrev_b64 v[90:91], 7, v[100:101]
	v_add_u32_e32 v102, 0xa0, v180
	v_ashrrev_i32_e32 v103, 31, v102
	v_lshlrev_b64 v[92:93], 7, v[102:103]
	v_add_u32_e32 v104, 0xb0, v180
	v_ashrrev_i32_e32 v105, 31, v104
	v_lshlrev_b64 v[94:95], 7, v[104:105]
	v_lshlrev_b64 v[118:119], 12, v[64:65]
	v_lshl_add_u64 v[64:65], v[182:183], 0, v[118:119]
	s_waitcnt vmcnt(6) lgkmcnt(0)
	v_mov_b32_e32 v66, v110
	v_mov_b32_e32 v67, v111
	v_mov_b32_e32 v68, v112
	v_mov_b32_e32 v69, v113
	v_mov_b32_e32 v70, v114
	v_mov_b32_e32 v71, v115
	v_mov_b32_e32 v72, v116
	v_mov_b32_e32 v73, v117
	v_mov_b32_e32 v74, v66
	v_mov_b32_e32 v75, v70
	v_mov_b32_e32 v70, v67
	v_pk_add_f32 v[66:67], v[74:75], v[70:71]
	v_mov_b32_e32 v70, v68
	v_mov_b32_e32 v71, v72
	v_mov_b32_e32 v72, v69
	v_pk_add_f32 v[68:69], v[70:71], v[72:73]
	s_nop 0
	v_pk_add_f32 v[66:67], v[66:67], v[68:69]
	s_nop 0
	v_add_f32_e32 v66, v66, v67
	ds_bpermute_b32 v67, v212, v66
	s_waitcnt lgkmcnt(0)
	v_add_f32_e32 v66, v66, v67
	ds_bpermute_b32 v67, v213, v66
	s_waitcnt lgkmcnt(0)
	v_add_f32_e32 v66, v66, v67
	v_fmamk_f32 v66, v66, 0x3a000000, v195
	v_div_scale_f32 v67, s[28:29], v66, v66, 1.0
	v_rcp_f32_e32 v68, v67
	s_nop 0
	v_fma_f32 v69, -v67, v68, 1.0
	v_fmac_f32_e32 v68, v69, v68
	v_div_scale_f32 v69, vcc, 1.0, v66, 1.0
	v_mul_f32_e32 v70, v69, v68
	v_fma_f32 v71, -v67, v70, v69
	v_fmac_f32_e32 v70, v71, v68
	v_fma_f32 v67, -v67, v70, v69
	v_div_fmas_f32 v67, v67, v68, v70
	v_lshl_add_u64 v[70:71], v[172:173], 0, v[90:91]
	v_div_fixup_f32 v106, v67, v66, 1.0
	s_nop 0
	s_nop 0
	s_nop 0
	s_waitcnt vmcnt(4) lgkmcnt(0)
	v_mov_b32_e32 v66, v120
	v_mov_b32_e32 v67, v121
	v_mov_b32_e32 v68, v122
	v_mov_b32_e32 v69, v123
	v_mov_b32_e32 v70, v124
	v_mov_b32_e32 v71, v125
	v_mov_b32_e32 v72, v126
	v_mov_b32_e32 v73, v127
	v_mov_b32_e32 v74, v66
	v_mov_b32_e32 v75, v70
	v_mov_b32_e32 v70, v67
	v_pk_add_f32 v[66:67], v[74:75], v[70:71]
	v_mov_b32_e32 v70, v68
	v_mov_b32_e32 v71, v72
	v_mov_b32_e32 v72, v69
	v_pk_add_f32 v[68:69], v[70:71], v[72:73]
	s_nop 0
	v_pk_add_f32 v[66:67], v[66:67], v[68:69]
	s_nop 0
	v_add_f32_e32 v66, v66, v67
	ds_bpermute_b32 v67, v212, v66
	s_waitcnt lgkmcnt(0)
	v_add_f32_e32 v66, v66, v67
	ds_bpermute_b32 v67, v213, v66
	s_waitcnt lgkmcnt(0)
	v_add_f32_e32 v66, v66, v67
	v_fmamk_f32 v66, v66, 0x3a000000, v195
	v_div_scale_f32 v67, s[28:29], v66, v66, 1.0
	v_rcp_f32_e32 v68, v67
	s_nop 0
	v_fma_f32 v69, -v67, v68, 1.0
	v_fmac_f32_e32 v68, v69, v68
	v_div_scale_f32 v69, vcc, 1.0, v66, 1.0
	v_mul_f32_e32 v70, v69, v68
	v_fma_f32 v71, -v67, v70, v69
	v_fmac_f32_e32 v70, v71, v68
	v_fma_f32 v67, -v67, v70, v69
	v_div_fmas_f32 v67, v67, v68, v70
	v_lshl_add_u64 v[70:71], v[172:173], 0, v[92:93]
	v_div_fixup_f32 v96, v67, v66, 1.0
	s_nop 0
	s_nop 0
	s_nop 0
	s_waitcnt vmcnt(2) lgkmcnt(0)
	v_mov_b32_e32 v66, v226
	v_mov_b32_e32 v67, v227
	v_mov_b32_e32 v68, v228
	v_mov_b32_e32 v69, v229
	v_mov_b32_e32 v70, v230
	v_mov_b32_e32 v71, v231
	v_mov_b32_e32 v72, v232
	v_mov_b32_e32 v73, v233
	v_mov_b32_e32 v74, v66
	v_mov_b32_e32 v75, v70
	v_mov_b32_e32 v70, v67
	v_pk_add_f32 v[66:67], v[74:75], v[70:71]
	v_mov_b32_e32 v70, v68
	v_mov_b32_e32 v71, v72
	v_mov_b32_e32 v72, v69
	v_pk_add_f32 v[68:69], v[70:71], v[72:73]
	s_nop 0
	v_pk_add_f32 v[66:67], v[66:67], v[68:69]
	s_nop 0
	v_add_f32_e32 v66, v66, v67
	ds_bpermute_b32 v67, v212, v66
	s_waitcnt lgkmcnt(0)
	v_add_f32_e32 v66, v66, v67
	ds_bpermute_b32 v67, v213, v66
	s_waitcnt lgkmcnt(0)
	v_add_f32_e32 v66, v66, v67
	v_fmamk_f32 v66, v66, 0x3a000000, v195
	v_div_scale_f32 v67, s[28:29], v66, v66, 1.0
	v_rcp_f32_e32 v68, v67
	s_nop 0
	v_fma_f32 v69, -v67, v68, 1.0
	v_fmac_f32_e32 v68, v69, v68
	v_div_scale_f32 v69, vcc, 1.0, v66, 1.0
	v_mul_f32_e32 v70, v69, v68
	v_fma_f32 v71, -v67, v70, v69
	v_fmac_f32_e32 v70, v71, v68
	v_fma_f32 v67, -v67, v70, v69
	v_div_fmas_f32 v67, v67, v68, v70
	v_lshl_add_u64 v[70:71], v[172:173], 0, v[94:95]
	v_div_fixup_f32 v98, v67, v66, 1.0
	s_nop 0
	s_nop 0
	s_nop 0
	s_waitcnt vmcnt(0) lgkmcnt(0)
	v_mov_b32_e32 v66, v240
	v_mov_b32_e32 v67, v241
	v_mov_b32_e32 v68, v242
	v_mov_b32_e32 v69, v243
	v_mov_b32_e32 v70, v244
	v_mov_b32_e32 v71, v245
	v_mov_b32_e32 v72, v246
	v_mov_b32_e32 v73, v247
	v_mov_b32_e32 v74, v66
	v_mov_b32_e32 v75, v70
	v_mov_b32_e32 v70, v67
	v_pk_add_f32 v[66:67], v[74:75], v[70:71]
	v_mov_b32_e32 v70, v68
	v_mov_b32_e32 v71, v72
	v_mov_b32_e32 v72, v69
	v_pk_add_f32 v[68:69], v[70:71], v[72:73]
	s_nop 0
	v_pk_add_f32 v[66:67], v[66:67], v[68:69]
	s_nop 0
	v_add_f32_e32 v66, v66, v67
	ds_bpermute_b32 v67, v212, v66
	s_waitcnt lgkmcnt(0)
	v_add_f32_e32 v66, v66, v67
	ds_bpermute_b32 v67, v213, v66
	s_waitcnt lgkmcnt(0)
	v_add_f32_e32 v66, v66, v67
	v_fmamk_f32 v66, v66, 0x3a000000, v195
	v_div_scale_f32 v67, s[28:29], v66, v66, 1.0
	v_rcp_f32_e32 v68, v67
	s_nop 0
	v_fma_f32 v69, -v67, v68, 1.0
	v_fmac_f32_e32 v68, v69, v68
	v_div_scale_f32 v69, vcc, 1.0, v66, 1.0
	v_mul_f32_e32 v70, v69, v68
	v_fma_f32 v71, -v67, v70, v69
	v_fmac_f32_e32 v70, v71, v68
	v_fma_f32 v67, -v67, v70, v69
	v_div_fmas_f32 v67, v67, v68, v70
	v_div_fixup_f32 v108, v67, v66, 1.0
	flat_load_dwordx4 v[110:113], v[64:65]
	flat_load_dwordx4 v[114:117], v[64:65] offset:256
	v_lshlrev_b64 v[64:65], 12, v[100:101]
	v_lshl_add_u64 v[64:65], v[182:183], 0, v[64:65]
	flat_load_dwordx4 v[84:87], v[64:65]
	flat_load_dwordx4 v[80:83], v[64:65] offset:256
	v_lshlrev_b64 v[64:65], 12, v[102:103]
	v_lshl_add_u64 v[64:65], v[182:183], 0, v[64:65]
	flat_load_dwordx4 v[76:79], v[64:65]
	flat_load_dwordx4 v[72:75], v[64:65] offset:256
	v_lshlrev_b64 v[64:65], 12, v[104:105]
	v_lshl_add_u64 v[64:65], v[182:183], 0, v[64:65]
	flat_load_dwordx4 v[68:71], v[64:65]
	s_nop 0
	flat_load_dwordx4 v[64:67], v[64:65] offset:256
	s_waitcnt vmcnt(0) lgkmcnt(0)
	v_lshlrev_b32_e32 v120, 16, v110
	v_and_b32_e32 v121, 0xffff0000, v110
	v_lshlrev_b32_e32 v110, 16, v111
	v_and_b32_e32 v111, 0xffff0000, v111
	v_lshlrev_b32_e32 v122, 16, v112
	v_and_b32_e32 v123, 0xffff0000, v112
	v_lshlrev_b32_e32 v112, 16, v113
	v_and_b32_e32 v113, 0xffff0000, v113
	v_pk_fma_f32 v[62:63], v[62:63], v[106:107], v[110:111] op_sel_hi:[1,0,1]
	v_pk_fma_f32 v[60:61], v[60:61], v[106:107], v[120:121] op_sel_hi:[1,0,1]
	v_pk_fma_f32 v[110:111], v[58:59], v[106:107], v[112:113] op_sel_hi:[1,0,1]
	v_mul_f32_e32 v58, v61, v61
	v_mul_f32_e32 v59, v63, v63
	v_pk_fma_f32 v[56:57], v[56:57], v[106:107], v[122:123] op_sel_hi:[1,0,1]
	v_fmac_f32_e32 v58, v60, v60
	v_fmac_f32_e32 v59, v62, v62
	v_add_f32_e32 v58, v58, v59
	v_mul_f32_e32 v59, v57, v57
	v_mul_f32_e32 v97, v111, v111
	v_fmac_f32_e32 v59, v56, v56
	v_fmac_f32_e32 v97, v110, v110
	v_add_f32_e32 v59, v59, v97
	v_add_f32_e32 v97, v58, v59
	v_cvt_pk_bf16_f32 v58, v60, v61
	v_cvt_pk_bf16_f32 v59, v62, v63
	v_cvt_pk_bf16_f32 v60, v56, v57
	v_lshl_add_u64 v[56:57], s[12:13], 0, v[118:119]
	v_cvt_pk_bf16_f32 v61, v110, v111
	v_lshl_add_u64 v[56:57], v[178:179], 1, v[56:57]
	flat_store_dwordx4 v[56:57], v[58:61]
	v_lshlrev_b32_e32 v62, 16, v116
	v_and_b32_e32 v63, 0xffff0000, v116
	v_lshlrev_b32_e32 v58, 16, v114
	v_and_b32_e32 v59, 0xffff0000, v114
	v_lshlrev_b32_e32 v60, 16, v115
	v_and_b32_e32 v61, 0xffff0000, v115
	v_lshlrev_b32_e32 v110, 16, v117
	v_and_b32_e32 v111, 0xffff0000, v117
	v_pk_fma_f32 v[54:55], v[54:55], v[106:107], v[60:61] op_sel_hi:[1,0,1]
	v_pk_fma_f32 v[52:53], v[52:53], v[106:107], v[58:59] op_sel_hi:[1,0,1]
	v_pk_fma_f32 v[58:59], v[50:51], v[106:107], v[110:111] op_sel_hi:[1,0,1]
	v_pk_fma_f32 v[50:51], v[48:49], v[106:107], v[62:63] op_sel_hi:[1,0,1]
	v_mul_f32_e32 v48, v53, v53
	v_mul_f32_e32 v49, v55, v55
	v_fmac_f32_e32 v48, v52, v52
	v_fmac_f32_e32 v49, v54, v54
	v_add_f32_e32 v48, v48, v49
	v_mul_f32_e32 v49, v51, v51
	v_mul_f32_e32 v60, v59, v59
	v_fmac_f32_e32 v49, v50, v50
	v_fmac_f32_e32 v60, v58, v58
	v_add_f32_e32 v49, v49, v60
	v_add_f32_e32 v48, v48, v49
	v_add_f32_e32 v60, v97, v48
	v_cvt_pk_bf16_f32 v48, v52, v53
	v_cvt_pk_bf16_f32 v49, v54, v55
	v_cvt_pk_bf16_f32 v50, v50, v51
	v_cvt_pk_bf16_f32 v51, v58, v59
	flat_store_dwordx4 v[56:57], v[48:51] offset:256
	ds_bpermute_b32 v48, v212, v60
	s_waitcnt lgkmcnt(0)
	v_add_f32_e32 v48, v60, v48
	ds_bpermute_b32 v49, v213, v48
	s_and_saveexec_b64 s[28:29], s[0:1]
	s_cbranch_execz .LBB0_929
	v_lshl_add_u64 v[50:51], s[14:15], 0, v[88:89]
	v_lshl_add_u64 v[50:51], s[26:27], 2, v[50:51]
	s_lshl_b32 s38, s61, 2
	v_lshl_add_u64 v[50:51], v[50:51], 0, s[38:39]
	s_waitcnt lgkmcnt(0)
	v_add_f32_e32 v48, v48, v49
	flat_store_dword v[50:51], v48

.LBB0_961:
	v_lshl_add_u32 v170, s20, 8, v175
	v_ashrrev_i32_e32 v171, 31, v170
	v_lshlrev_b64 v[128:129], 7, v[170:171]
	v_lshl_add_u64 v[132:133], v[154:155], 0, v[128:129]
	global_load_dwordx4 v[214:217], v[132:133], off
	global_load_dwordx4 v[218:221], v[132:133], off offset:16
	global_load_dwordx4 v[222:225], v[132:133], off offset:2048
	global_load_dwordx4 v[226:229], v[132:133], off offset:2064
	v_add_co_u32_e32 v234, vcc, 0x1000, v132
	s_nop 1
	v_addc_co_u32_e32 v235, vcc, 0, v133, vcc
	global_load_dwordx4 v[230:233], v[234:235], off
	global_load_dwordx4 v[240:243], v[234:235], off offset:16
	global_load_dwordx4 v[244:247], v[234:235], off offset:2048
	global_load_dwordx4 v[248:251], v[234:235], off offset:2064
	s_nop 0
	s_nop 0
	v_lshl_or_b32 v176, s21, 8, v189
	v_or_b32_e32 v180, 16, v170
	v_ashrrev_i32_e32 v181, 31, v180
	v_or_b32_e32 v184, 32, v170
	v_ashrrev_i32_e32 v185, 31, v184
	v_or_b32_e32 v186, 48, v170
	v_ashrrev_i32_e32 v187, 31, v186
	v_ashrrev_i32_e32 v177, 31, v176
	v_lshl_add_u64 v[172:173], v[176:177], 1, s[8:9]
	s_waitcnt vmcnt(6) lgkmcnt(0)
	v_mov_b32_e32 v128, v214
	v_mov_b32_e32 v129, v215
	v_mov_b32_e32 v130, v216
	v_mov_b32_e32 v131, v217
	v_mov_b32_e32 v132, v218
	v_mov_b32_e32 v133, v219
	v_mov_b32_e32 v134, v220
	v_mov_b32_e32 v135, v221
	v_mov_b32_e32 v136, v128
	v_mov_b32_e32 v137, v132
	v_mov_b32_e32 v132, v129
	v_pk_add_f32 v[128:129], v[136:137], v[132:133]
	v_mov_b32_e32 v132, v130
	v_mov_b32_e32 v133, v134
	v_mov_b32_e32 v134, v131
	v_pk_add_f32 v[130:131], v[132:133], v[134:135]
	s_nop 0
	v_pk_add_f32 v[128:129], v[128:129], v[130:131]
	v_and_b32_e32 v130, 64, v236
	v_add_f32_e32 v128, v128, v129
	v_xor_b32_e32 v129, 16, v236
	v_add_u32_e32 v130, 64, v130
	v_cmp_lt_i32_e32 vcc, v129, v130
	s_nop 1
	v_cndmask_b32_e32 v129, v236, v129, vcc
	v_lshlrev_b32_e32 v191, 2, v129
	ds_bpermute_b32 v129, v191, v128
	s_waitcnt lgkmcnt(0)
	v_add_f32_e32 v128, v128, v129
	v_xor_b32_e32 v129, 32, v236
	v_cmp_lt_i32_e32 vcc, v129, v130
	s_nop 1
	v_cndmask_b32_e32 v129, v236, v129, vcc
	v_lshlrev_b32_e32 v190, 2, v129
	ds_bpermute_b32 v129, v190, v128
	s_waitcnt lgkmcnt(0)
	v_add_f32_e32 v128, v128, v129
	v_fmamk_f32 v128, v128, 0x3a000000, v195
	v_div_scale_f32 v129, s[20:21], v128, v128, 1.0
	v_rcp_f32_e32 v130, v129
	s_nop 0
	v_fma_f32 v131, -v129, v130, 1.0
	v_fmac_f32_e32 v130, v131, v130
	v_div_scale_f32 v131, vcc, 1.0, v128, 1.0
	v_mul_f32_e32 v132, v131, v130
	v_fma_f32 v133, -v129, v132, v131
	v_fmac_f32_e32 v132, v133, v130
	v_fma_f32 v129, -v129, v132, v131
	v_div_fmas_f32 v129, v129, v130, v132
	v_div_fixup_f32 v174, v129, v128, 1.0
	v_lshlrev_b64 v[128:129], 7, v[180:181]
	v_lshl_add_u64 v[132:133], v[154:155], 0, v[128:129]
	s_nop 0
	s_nop 0
	s_nop 0
	s_waitcnt vmcnt(4) lgkmcnt(0)
	v_mov_b32_e32 v128, v222
	v_mov_b32_e32 v129, v223
	v_mov_b32_e32 v130, v224
	v_mov_b32_e32 v131, v225
	v_mov_b32_e32 v132, v226
	v_mov_b32_e32 v133, v227
	v_mov_b32_e32 v134, v228
	v_mov_b32_e32 v135, v229
	v_mov_b32_e32 v136, v128
	v_mov_b32_e32 v137, v132
	v_mov_b32_e32 v132, v129
	v_pk_add_f32 v[128:129], v[136:137], v[132:133]
	v_mov_b32_e32 v132, v130
	v_mov_b32_e32 v133, v134
	v_mov_b32_e32 v134, v131
	v_pk_add_f32 v[130:131], v[132:133], v[134:135]
	s_nop 0
	v_pk_add_f32 v[128:129], v[128:129], v[130:131]
	s_nop 0
	v_add_f32_e32 v128, v128, v129
	ds_bpermute_b32 v129, v191, v128
	s_waitcnt lgkmcnt(0)
	v_add_f32_e32 v128, v128, v129
	ds_bpermute_b32 v129, v190, v128
	s_waitcnt lgkmcnt(0)
	v_add_f32_e32 v128, v128, v129
	v_fmamk_f32 v128, v128, 0x3a000000, v195
	v_div_scale_f32 v129, s[20:21], v128, v128, 1.0
	v_rcp_f32_e32 v130, v129
	s_nop 0
	v_fma_f32 v131, -v129, v130, 1.0
	v_fmac_f32_e32 v130, v131, v130
	v_div_scale_f32 v131, vcc, 1.0, v128, 1.0
	v_mul_f32_e32 v132, v131, v130
	v_fma_f32 v133, -v129, v132, v131
	v_fmac_f32_e32 v132, v133, v130
	v_fma_f32 v129, -v129, v132, v131
	v_div_fmas_f32 v129, v129, v130, v132
	v_div_fixup_f32 v178, v129, v128, 1.0
	v_lshlrev_b64 v[128:129], 7, v[184:185]
	v_lshl_add_u64 v[132:133], v[154:155], 0, v[128:129]
	s_nop 0
	s_nop 0
	s_nop 0
	s_waitcnt vmcnt(2) lgkmcnt(0)
	v_mov_b32_e32 v128, v230
	v_mov_b32_e32 v129, v231
	v_mov_b32_e32 v130, v232
	v_mov_b32_e32 v131, v233
	v_mov_b32_e32 v132, v240
	v_mov_b32_e32 v133, v241
	v_mov_b32_e32 v134, v242
	v_mov_b32_e32 v135, v243
	v_mov_b32_e32 v136, v128
	v_mov_b32_e32 v137, v132
	v_mov_b32_e32 v132, v129
	v_pk_add_f32 v[128:129], v[136:137], v[132:133]
	v_mov_b32_e32 v132, v130
	v_mov_b32_e32 v133, v134
	v_mov_b32_e32 v134, v131
	v_pk_add_f32 v[130:131], v[132:133], v[134:135]
	s_nop 0
	v_pk_add_f32 v[128:129], v[128:129], v[130:131]
	s_nop 0
	v_add_f32_e32 v128, v128, v129
	ds_bpermute_b32 v129, v191, v128
	s_waitcnt lgkmcnt(0)
	v_add_f32_e32 v128, v128, v129
	ds_bpermute_b32 v129, v190, v128
	s_waitcnt lgkmcnt(0)
	v_add_f32_e32 v128, v128, v129
	v_fmamk_f32 v128, v128, 0x3a000000, v195
	v_div_scale_f32 v129, s[20:21], v128, v128, 1.0
	v_rcp_f32_e32 v130, v129
	s_nop 0
	v_fma_f32 v131, -v129, v130, 1.0
	v_fmac_f32_e32 v130, v131, v130
	v_div_scale_f32 v131, vcc, 1.0, v128, 1.0
	v_mul_f32_e32 v132, v131, v130
	v_fma_f32 v133, -v129, v132, v131
	v_fmac_f32_e32 v132, v133, v130
	v_fma_f32 v129, -v129, v132, v131
	v_div_fmas_f32 v129, v129, v130, v132
	v_div_fixup_f32 v182, v129, v128, 1.0
	v_lshlrev_b64 v[128:129], 7, v[186:187]
	v_lshl_add_u64 v[128:129], v[154:155], 0, v[128:129]
	s_nop 0
	s_nop 0
	s_nop 0
	s_waitcnt vmcnt(0) lgkmcnt(0)
	v_mov_b32_e32 v132, v244
	v_mov_b32_e32 v133, v245
	v_mov_b32_e32 v134, v246
	v_mov_b32_e32 v135, v247
	v_mov_b32_e32 v128, v248
	v_mov_b32_e32 v129, v249
	v_mov_b32_e32 v130, v250
	v_mov_b32_e32 v131, v251
	v_mov_b32_e32 v136, v132
	v_mov_b32_e32 v137, v128
	v_mov_b32_e32 v128, v133
	v_mov_b32_e32 v132, v134
	v_mov_b32_e32 v133, v130
	v_mov_b32_e32 v130, v135
	v_pk_add_f32 v[128:129], v[136:137], v[128:129]
	v_pk_add_f32 v[130:131], v[132:133], v[130:131]
	s_nop 0
	v_pk_add_f32 v[128:129], v[128:129], v[130:131]
	s_nop 0
	v_add_f32_e32 v128, v128, v129
	ds_bpermute_b32 v129, v191, v128
	s_waitcnt lgkmcnt(0)
	v_add_f32_e32 v128, v128, v129
	ds_bpermute_b32 v129, v190, v128
	s_waitcnt lgkmcnt(0)
	v_add_f32_e32 v128, v128, v129
	v_fmamk_f32 v128, v128, 0x3a000000, v195
	v_div_scale_f32 v129, s[20:21], v128, v128, 1.0
	v_rcp_f32_e32 v130, v129
	s_nop 0
	v_fma_f32 v131, -v129, v130, 1.0
	v_fmac_f32_e32 v130, v131, v130
	v_div_scale_f32 v131, vcc, 1.0, v128, 1.0
	v_mul_f32_e32 v132, v131, v130
	v_fma_f32 v133, -v129, v132, v131
	v_fmac_f32_e32 v132, v133, v130
	v_fma_f32 v129, -v129, v132, v131
	v_div_fmas_f32 v129, v129, v130, v132
	v_div_fixup_f32 v188, v129, v128, 1.0
	v_lshlrev_b64 v[128:129], 12, v[170:171]
	v_lshl_add_u64 v[128:129], v[172:173], 0, v[128:129]
	flat_load_dwordx4 v[198:201], v[128:129]
	flat_load_dwordx4 v[202:205], v[128:129] offset:256
	v_lshlrev_b64 v[128:129], 12, v[180:181]
	v_lshl_add_u64 v[128:129], v[172:173], 0, v[128:129]
	flat_load_dwordx4 v[210:213], v[128:129]
	flat_load_dwordx4 v[144:147], v[128:129] offset:256
	v_lshlrev_b64 v[128:129], 12, v[184:185]
	v_lshl_add_u64 v[128:129], v[172:173], 0, v[128:129]
	flat_load_dwordx4 v[140:143], v[128:129]
	flat_load_dwordx4 v[136:139], v[128:129] offset:256
	v_lshlrev_b64 v[128:129], 12, v[186:187]
	v_lshl_add_u64 v[128:129], v[172:173], 0, v[128:129]
	flat_load_dwordx4 v[132:135], v[128:129]
	s_nop 0
	flat_load_dwordx4 v[128:131], v[128:129] offset:256
	s_waitcnt vmcnt(0) lgkmcnt(0)
	v_lshlrev_b32_e32 v206, 16, v198
	v_and_b32_e32 v207, 0xffff0000, v198
	v_lshlrev_b32_e32 v198, 16, v199
	v_and_b32_e32 v199, 0xffff0000, v199
	v_lshlrev_b32_e32 v208, 16, v200
	v_and_b32_e32 v209, 0xffff0000, v200
	v_lshlrev_b32_e32 v200, 16, v201
	v_and_b32_e32 v201, 0xffff0000, v201
	v_pk_fma_f32 v[126:127], v[126:127], v[174:175], v[198:199] op_sel_hi:[1,0,1]
	v_pk_fma_f32 v[198:199], v[120:121], v[174:175], v[208:209] op_sel_hi:[1,0,1]
	v_lshlrev_b64 v[120:121], 13, v[170:171]
	v_pk_fma_f32 v[200:201], v[122:123], v[174:175], v[200:201] op_sel_hi:[1,0,1]
	v_lshl_add_u64 v[122:123], s[4:5], 0, v[120:121]
	v_lshlrev_b64 v[120:121], 2, v[176:177]
	v_pk_fma_f32 v[124:125], v[124:125], v[174:175], v[206:207] op_sel_hi:[1,0,1]
	v_lshl_add_u64 v[122:123], v[122:123], 0, v[120:121]
	flat_store_dwordx4 v[122:123], v[124:127]
	flat_store_dwordx4 v[122:123], v[198:201] offset:16
	v_lshlrev_b32_e32 v176, 16, v204
	v_lshlrev_b32_e32 v124, 16, v202
	v_and_b32_e32 v125, 0xffff0000, v202
	v_lshlrev_b32_e32 v126, 16, v203
	v_and_b32_e32 v127, 0xffff0000, v203
	v_and_b32_e32 v177, 0xffff0000, v204
	v_lshlrev_b32_e32 v198, 16, v205
	v_and_b32_e32 v199, 0xffff0000, v205
	v_pk_fma_f32 v[118:119], v[118:119], v[174:175], v[126:127] op_sel_hi:[1,0,1]
	v_pk_fma_f32 v[116:117], v[116:117], v[174:175], v[124:125] op_sel_hi:[1,0,1]
	v_pk_fma_f32 v[112:113], v[112:113], v[174:175], v[176:177] op_sel_hi:[1,0,1]
	v_pk_fma_f32 v[114:115], v[114:115], v[174:175], v[198:199] op_sel_hi:[1,0,1]
	flat_store_dwordx4 v[122:123], v[116:119] offset:512
	flat_store_dwordx4 v[122:123], v[112:115] offset:528
	s_nop 0
	v_lshlrev_b32_e32 v116, 16, v212
	v_lshlrev_b32_e32 v112, 16, v210
	v_and_b32_e32 v113, 0xffff0000, v210
	v_pk_fma_f32 v[108:109], v[108:109], v[178:179], v[112:113] op_sel_hi:[1,0,1]
	v_lshlrev_b64 v[112:113], 13, v[180:181]
	v_lshlrev_b32_e32 v114, 16, v211
	v_and_b32_e32 v115, 0xffff0000, v211
	v_and_b32_e32 v117, 0xffff0000, v212
	v_lshlrev_b32_e32 v118, 16, v213
	v_and_b32_e32 v119, 0xffff0000, v213
	v_lshl_add_u64 v[112:113], s[4:5], 0, v[112:113]
	v_pk_fma_f32 v[110:111], v[110:111], v[178:179], v[114:115] op_sel_hi:[1,0,1]
	v_pk_fma_f32 v[106:107], v[106:107], v[178:179], v[118:119] op_sel_hi:[1,0,1]
	v_pk_fma_f32 v[104:105], v[104:105], v[178:179], v[116:117] op_sel_hi:[1,0,1]
	v_lshl_add_u64 v[112:113], v[112:113], 0, v[120:121]
	flat_store_dwordx4 v[112:113], v[108:111]
	flat_store_dwordx4 v[112:113], v[104:107] offset:16
	s_nop 0
	v_lshlrev_b32_e32 v108, 16, v146
	v_lshlrev_b32_e32 v104, 16, v144
	v_and_b32_e32 v105, 0xffff0000, v144
	v_lshlrev_b32_e32 v106, 16, v145
	v_and_b32_e32 v107, 0xffff0000, v145
	v_and_b32_e32 v109, 0xffff0000, v146
	v_lshlrev_b32_e32 v110, 16, v147
	v_and_b32_e32 v111, 0xffff0000, v147
	v_pk_fma_f32 v[102:103], v[102:103], v[178:179], v[106:107] op_sel_hi:[1,0,1]
	v_pk_fma_f32 v[100:101], v[100:101], v[178:179], v[104:105] op_sel_hi:[1,0,1]
	v_pk_fma_f32 v[92:93], v[92:93], v[178:179], v[108:109] op_sel_hi:[1,0,1]
	v_pk_fma_f32 v[94:95], v[94:95], v[178:179], v[110:111] op_sel_hi:[1,0,1]
	flat_store_dwordx4 v[112:113], v[100:103] offset:512
	flat_store_dwordx4 v[112:113], v[92:95] offset:528
	s_nop 0
	v_lshlrev_b32_e32 v100, 16, v142
	v_lshlrev_b32_e32 v92, 16, v140
	v_and_b32_e32 v93, 0xffff0000, v140
	v_pk_fma_f32 v[92:93], v[96:97], v[182:183], v[92:93] op_sel_hi:[1,0,1]
	v_lshlrev_b64 v[96:97], 13, v[184:185]
	v_lshlrev_b32_e32 v94, 16, v141
	v_and_b32_e32 v95, 0xffff0000, v141
	v_and_b32_e32 v101, 0xffff0000, v142
	v_lshlrev_b32_e32 v102, 16, v143
	v_and_b32_e32 v103, 0xffff0000, v143
	v_lshl_add_u64 v[96:97], s[4:5], 0, v[96:97]
	v_pk_fma_f32 v[94:95], v[98:99], v[182:183], v[94:95] op_sel_hi:[1,0,1]
	v_pk_fma_f32 v[90:91], v[90:91], v[182:183], v[102:103] op_sel_hi:[1,0,1]
	v_pk_fma_f32 v[88:89], v[88:89], v[182:183], v[100:101] op_sel_hi:[1,0,1]
	v_lshl_add_u64 v[96:97], v[96:97], 0, v[120:121]
	flat_store_dwordx4 v[96:97], v[92:95]
	flat_store_dwordx4 v[96:97], v[88:91] offset:16
	s_nop 0
	v_lshlrev_b32_e32 v92, 16, v138
	v_lshlrev_b32_e32 v88, 16, v136
	v_and_b32_e32 v89, 0xffff0000, v136
	v_lshlrev_b32_e32 v90, 16, v137
	v_and_b32_e32 v91, 0xffff0000, v137
	v_and_b32_e32 v93, 0xffff0000, v138
	v_lshlrev_b32_e32 v94, 16, v139
	v_and_b32_e32 v95, 0xffff0000, v139
	v_pk_fma_f32 v[86:87], v[86:87], v[182:183], v[90:91] op_sel_hi:[1,0,1]
	v_pk_fma_f32 v[84:85], v[84:85], v[182:183], v[88:89] op_sel_hi:[1,0,1]
	v_pk_fma_f32 v[76:77], v[76:77], v[182:183], v[92:93] op_sel_hi:[1,0,1]
	v_pk_fma_f32 v[78:79], v[78:79], v[182:183], v[94:95] op_sel_hi:[1,0,1]
	flat_store_dwordx4 v[96:97], v[84:87] offset:512
	flat_store_dwordx4 v[96:97], v[76:79] offset:528
	s_nop 0
	v_lshlrev_b32_e32 v86, 16, v135
	v_lshlrev_b32_e32 v76, 16, v132
	v_and_b32_e32 v77, 0xffff0000, v132
	v_pk_fma_f32 v[76:77], v[80:81], v[188:189], v[76:77] op_sel_hi:[1,0,1]
	v_lshlrev_b64 v[80:81], 13, v[186:187]
	v_lshlrev_b32_e32 v78, 16, v133
	v_and_b32_e32 v79, 0xffff0000, v133
	v_and_b32_e32 v87, 0xffff0000, v135
	v_lshl_add_u64 v[80:81], s[4:5], 0, v[80:81]
	v_lshlrev_b32_e32 v84, 16, v134
	v_and_b32_e32 v85, 0xffff0000, v134
	v_pk_fma_f32 v[78:79], v[82:83], v[188:189], v[78:79] op_sel_hi:[1,0,1]
	v_pk_fma_f32 v[74:75], v[74:75], v[188:189], v[86:87] op_sel_hi:[1,0,1]
	v_lshl_add_u64 v[80:81], v[80:81], 0, v[120:121]
	v_pk_fma_f32 v[72:73], v[72:73], v[188:189], v[84:85] op_sel_hi:[1,0,1]
	flat_store_dwordx4 v[80:81], v[76:79]
	flat_store_dwordx4 v[80:81], v[72:75] offset:16
	v_add_u32_e32 v82, 0xa0, v170
	v_lshlrev_b32_e32 v76, 16, v130
	v_lshlrev_b32_e32 v74, 16, v129
	v_and_b32_e32 v75, 0xffff0000, v129
	v_lshlrev_b32_e32 v72, 16, v128
	v_and_b32_e32 v73, 0xffff0000, v128
	v_and_b32_e32 v77, 0xffff0000, v130
	v_pk_fma_f32 v[70:71], v[70:71], v[188:189], v[74:75] op_sel_hi:[1,0,1]
	v_add_u32_e32 v74, 0x80, v170
	v_lshlrev_b32_e32 v78, 16, v131
	v_and_b32_e32 v79, 0xffff0000, v131
	v_pk_fma_f32 v[68:69], v[68:69], v[188:189], v[72:73] op_sel_hi:[1,0,1]
	v_pk_fma_f32 v[64:65], v[64:65], v[188:189], v[76:77] op_sel_hi:[1,0,1]
	v_ashrrev_i32_e32 v75, 31, v74
	v_pk_fma_f32 v[66:67], v[66:67], v[188:189], v[78:79] op_sel_hi:[1,0,1]
	flat_store_dwordx4 v[80:81], v[68:71] offset:512
	flat_store_dwordx4 v[80:81], v[64:67] offset:528
	v_add_u32_e32 v78, 0x90, v170
	v_ashrrev_i32_e32 v79, 31, v78
	v_lshlrev_b64 v[64:65], 7, v[74:75]
	v_lshl_add_u64 v[68:69], v[154:155], 0, v[64:65]
	global_load_dwordx4 v[88:91], v[68:69], off
	global_load_dwordx4 v[92:95], v[68:69], off offset:16
	global_load_dwordx4 v[96:99], v[68:69], off offset:2048
	global_load_dwordx4 v[100:103], v[68:69], off offset:2064
	v_add_co_u32_e32 v234, vcc, 0x1000, v68
	s_nop 1
	v_addc_co_u32_e32 v235, vcc, 0, v69, vcc
	global_load_dwordx4 v[104:107], v[234:235], off
	global_load_dwordx4 v[108:111], v[234:235], off offset:16
	global_load_dwordx4 v[214:217], v[234:235], off offset:2048
	global_load_dwordx4 v[218:221], v[234:235], off offset:2064
	s_nop 0
	s_nop 0
	v_ashrrev_i32_e32 v83, 31, v82
	v_add_u32_e32 v84, 0xb0, v170
	v_ashrrev_i32_e32 v85, 31, v84
	s_waitcnt vmcnt(6) lgkmcnt(0)
	v_mov_b32_e32 v64, v88
	v_mov_b32_e32 v65, v89
	v_mov_b32_e32 v66, v90
	v_mov_b32_e32 v67, v91
	v_mov_b32_e32 v68, v92
	v_mov_b32_e32 v69, v93
	v_mov_b32_e32 v70, v94
	v_mov_b32_e32 v71, v95
	v_mov_b32_e32 v72, v64
	v_mov_b32_e32 v73, v68
	v_mov_b32_e32 v68, v65
	v_pk_add_f32 v[64:65], v[72:73], v[68:69]
	v_mov_b32_e32 v68, v66
	v_mov_b32_e32 v69, v70
	v_mov_b32_e32 v70, v67
	v_pk_add_f32 v[66:67], v[68:69], v[70:71]
	s_nop 0
	v_pk_add_f32 v[64:65], v[64:65], v[66:67]
	s_nop 0
	v_add_f32_e32 v64, v64, v65
	ds_bpermute_b32 v65, v191, v64
	s_waitcnt lgkmcnt(0)
	v_add_f32_e32 v64, v64, v65
	ds_bpermute_b32 v65, v190, v64
	s_waitcnt lgkmcnt(0)
	v_add_f32_e32 v64, v64, v65
	v_fmamk_f32 v64, v64, 0x3a000000, v195
	v_div_scale_f32 v65, s[20:21], v64, v64, 1.0
	v_rcp_f32_e32 v66, v65
	s_nop 0
	v_fma_f32 v67, -v65, v66, 1.0
	v_fmac_f32_e32 v66, v67, v66
	v_div_scale_f32 v67, vcc, 1.0, v64, 1.0
	v_mul_f32_e32 v68, v67, v66
	v_fma_f32 v69, -v65, v68, v67
	v_fmac_f32_e32 v68, v69, v66
	v_fma_f32 v65, -v65, v68, v67
	v_div_fmas_f32 v65, v65, v66, v68
	v_div_fixup_f32 v72, v65, v64, 1.0
	v_lshlrev_b64 v[64:65], 7, v[78:79]
	v_lshl_add_u64 v[68:69], v[154:155], 0, v[64:65]
	s_nop 0
	s_nop 0
	s_nop 0
	s_waitcnt vmcnt(4) lgkmcnt(0)
	v_mov_b32_e32 v64, v96
	v_mov_b32_e32 v65, v97
	v_mov_b32_e32 v66, v98
	v_mov_b32_e32 v67, v99
	v_mov_b32_e32 v68, v100
	v_mov_b32_e32 v69, v101
	v_mov_b32_e32 v70, v102
	v_mov_b32_e32 v71, v103
	v_mov_b32_e32 v76, v64
	v_mov_b32_e32 v77, v68
	v_mov_b32_e32 v68, v65
	v_pk_add_f32 v[64:65], v[76:77], v[68:69]
	v_mov_b32_e32 v68, v66
	v_mov_b32_e32 v69, v70
	v_mov_b32_e32 v70, v67
	v_pk_add_f32 v[66:67], v[68:69], v[70:71]
	s_nop 0
	v_pk_add_f32 v[64:65], v[64:65], v[66:67]
	s_nop 0
	v_add_f32_e32 v64, v64, v65
	ds_bpermute_b32 v65, v191, v64
	s_waitcnt lgkmcnt(0)
	v_add_f32_e32 v64, v64, v65
	ds_bpermute_b32 v65, v190, v64
	s_waitcnt lgkmcnt(0)
	v_add_f32_e32 v64, v64, v65
	v_fmamk_f32 v64, v64, 0x3a000000, v195
	v_div_scale_f32 v65, s[20:21], v64, v64, 1.0
	v_rcp_f32_e32 v66, v65
	s_nop 0
	v_fma_f32 v67, -v65, v66, 1.0
	v_fmac_f32_e32 v66, v67, v66
	v_div_scale_f32 v67, vcc, 1.0, v64, 1.0
	v_mul_f32_e32 v68, v67, v66
	v_fma_f32 v69, -v65, v68, v67
	v_fmac_f32_e32 v68, v69, v66
	v_fma_f32 v65, -v65, v68, v67
	v_div_fmas_f32 v65, v65, v66, v68
	v_div_fixup_f32 v76, v65, v64, 1.0
	v_lshlrev_b64 v[64:65], 7, v[82:83]
	v_lshl_add_u64 v[68:69], v[154:155], 0, v[64:65]
	s_nop 0
	s_nop 0
	s_nop 0
	s_waitcnt vmcnt(2) lgkmcnt(0)
	v_mov_b32_e32 v64, v104
	v_mov_b32_e32 v65, v105
	v_mov_b32_e32 v66, v106
	v_mov_b32_e32 v67, v107
	v_mov_b32_e32 v68, v108
	v_mov_b32_e32 v69, v109
	v_mov_b32_e32 v70, v110
	v_mov_b32_e32 v71, v111
	v_mov_b32_e32 v80, v64
	v_mov_b32_e32 v81, v68
	v_mov_b32_e32 v68, v65
	v_pk_add_f32 v[64:65], v[80:81], v[68:69]
	v_mov_b32_e32 v68, v66
	v_mov_b32_e32 v69, v70
	v_mov_b32_e32 v70, v67
	v_pk_add_f32 v[66:67], v[68:69], v[70:71]
	s_nop 0
	v_pk_add_f32 v[64:65], v[64:65], v[66:67]
	s_nop 0
	v_add_f32_e32 v64, v64, v65
	ds_bpermute_b32 v65, v191, v64
	s_waitcnt lgkmcnt(0)
	v_add_f32_e32 v64, v64, v65
	ds_bpermute_b32 v65, v190, v64
	s_waitcnt lgkmcnt(0)
	v_add_f32_e32 v64, v64, v65
	v_fmamk_f32 v64, v64, 0x3a000000, v195
	v_div_scale_f32 v65, s[20:21], v64, v64, 1.0
	v_rcp_f32_e32 v66, v65
	s_nop 0
	v_fma_f32 v67, -v65, v66, 1.0
	v_fmac_f32_e32 v66, v67, v66
	v_div_scale_f32 v67, vcc, 1.0, v64, 1.0
	v_mul_f32_e32 v68, v67, v66
	v_fma_f32 v69, -v65, v68, v67
	v_fmac_f32_e32 v68, v69, v66
	v_fma_f32 v65, -v65, v68, v67
	v_div_fmas_f32 v65, v65, v66, v68
	v_div_fixup_f32 v80, v65, v64, 1.0
	v_lshlrev_b64 v[64:65], 7, v[84:85]
	v_lshl_add_u64 v[64:65], v[154:155], 0, v[64:65]
	s_nop 0
	s_nop 0
	s_nop 0
	s_waitcnt vmcnt(0) lgkmcnt(0)
	v_mov_b32_e32 v68, v214
	v_mov_b32_e32 v69, v215
	v_mov_b32_e32 v70, v216
	v_mov_b32_e32 v71, v217
	v_mov_b32_e32 v64, v218
	v_mov_b32_e32 v65, v219
	v_mov_b32_e32 v66, v220
	v_mov_b32_e32 v67, v221
	v_mov_b32_e32 v86, v68
	v_mov_b32_e32 v87, v64
	v_mov_b32_e32 v64, v69
	v_mov_b32_e32 v68, v70
	v_mov_b32_e32 v69, v66
	v_mov_b32_e32 v66, v71
	v_pk_add_f32 v[64:65], v[86:87], v[64:65]
	v_pk_add_f32 v[66:67], v[68:69], v[66:67]
	s_nop 0
	v_pk_add_f32 v[64:65], v[64:65], v[66:67]
	s_nop 0
	v_add_f32_e32 v64, v64, v65
	ds_bpermute_b32 v65, v191, v64
	s_waitcnt lgkmcnt(0)
	v_add_f32_e32 v64, v64, v65
	ds_bpermute_b32 v65, v190, v64
	s_waitcnt lgkmcnt(0)
	v_add_f32_e32 v64, v64, v65
	v_fmamk_f32 v64, v64, 0x3a000000, v195
	v_div_scale_f32 v65, s[20:21], v64, v64, 1.0
	v_rcp_f32_e32 v66, v65
	s_mov_b64 s[20:21], -1
	v_fma_f32 v67, -v65, v66, 1.0
	v_fmac_f32_e32 v66, v67, v66
	v_div_scale_f32 v67, vcc, 1.0, v64, 1.0
	v_mul_f32_e32 v68, v67, v66
	v_fma_f32 v69, -v65, v68, v67
	v_fmac_f32_e32 v68, v69, v66
	v_fma_f32 v65, -v65, v68, v67
	v_div_fmas_f32 v65, v65, v66, v68
	v_div_fixup_f32 v68, v65, v64, 1.0
	v_lshlrev_b64 v[64:65], 12, v[74:75]
	v_lshl_add_u64 v[64:65], v[172:173], 0, v[64:65]
	flat_load_dwordx4 v[86:89], v[64:65]
	flat_load_dwordx4 v[90:93], v[64:65] offset:256
	v_lshlrev_b64 v[64:65], 12, v[78:79]
	v_lshl_add_u64 v[64:65], v[172:173], 0, v[64:65]
	flat_load_dwordx4 v[94:97], v[64:65]
	flat_load_dwordx4 v[98:101], v[64:65] offset:256
	v_lshlrev_b64 v[64:65], 12, v[82:83]
	v_lshl_add_u64 v[64:65], v[172:173], 0, v[64:65]
	flat_load_dwordx4 v[102:105], v[64:65]
	flat_load_dwordx4 v[106:109], v[64:65] offset:256
	v_lshlrev_b64 v[64:65], 12, v[84:85]
	v_lshl_add_u64 v[64:65], v[172:173], 0, v[64:65]
	flat_load_dwordx4 v[110:113], v[64:65]
	s_nop 0
	flat_load_dwordx4 v[64:67], v[64:65] offset:256
	s_andn2_b64 vcc, exec, s[0:1]
	s_waitcnt vmcnt(0) lgkmcnt(0)
	v_lshlrev_b32_e32 v70, 16, v86
	v_and_b32_e32 v71, 0xffff0000, v86
	v_pk_fma_f32 v[60:61], v[60:61], v[72:73], v[70:71] op_sel_hi:[1,0,1]
	v_lshlrev_b64 v[70:71], 13, v[74:75]
	v_lshlrev_b32_e32 v86, 16, v87
	v_and_b32_e32 v87, 0xffff0000, v87
	v_lshlrev_b32_e32 v114, 16, v88
	v_and_b32_e32 v115, 0xffff0000, v88
	v_lshlrev_b32_e32 v88, 16, v89
	v_and_b32_e32 v89, 0xffff0000, v89
	v_lshl_add_u64 v[70:71], s[4:5], 0, v[70:71]
	v_pk_fma_f32 v[62:63], v[62:63], v[72:73], v[86:87] op_sel_hi:[1,0,1]
	v_pk_fma_f32 v[58:59], v[58:59], v[72:73], v[88:89] op_sel_hi:[1,0,1]
	v_pk_fma_f32 v[56:57], v[56:57], v[72:73], v[114:115] op_sel_hi:[1,0,1]
	v_lshl_add_u64 v[70:71], v[70:71], 0, v[120:121]
	flat_store_dwordx4 v[70:71], v[60:63]
	flat_store_dwordx4 v[70:71], v[56:59] offset:16
	s_nop 0
	v_lshlrev_b32_e32 v60, 16, v92
	v_lshlrev_b32_e32 v56, 16, v90
	v_and_b32_e32 v57, 0xffff0000, v90
	v_lshlrev_b32_e32 v58, 16, v91
	v_and_b32_e32 v59, 0xffff0000, v91
	v_and_b32_e32 v61, 0xffff0000, v92
	v_lshlrev_b32_e32 v62, 16, v93
	v_and_b32_e32 v63, 0xffff0000, v93
	v_pk_fma_f32 v[54:55], v[54:55], v[72:73], v[58:59] op_sel_hi:[1,0,1]
	v_pk_fma_f32 v[52:53], v[52:53], v[72:73], v[56:57] op_sel_hi:[1,0,1]
	v_pk_fma_f32 v[44:45], v[44:45], v[72:73], v[60:61] op_sel_hi:[1,0,1]
	v_pk_fma_f32 v[46:47], v[46:47], v[72:73], v[62:63] op_sel_hi:[1,0,1]
	flat_store_dwordx4 v[70:71], v[52:55] offset:512
	flat_store_dwordx4 v[70:71], v[44:47] offset:528
	s_nop 0
	v_lshlrev_b32_e32 v52, 16, v96
	v_lshlrev_b32_e32 v44, 16, v94
	v_and_b32_e32 v45, 0xffff0000, v94
	v_pk_fma_f32 v[44:45], v[48:49], v[76:77], v[44:45] op_sel_hi:[1,0,1]
	v_lshlrev_b64 v[48:49], 13, v[78:79]
	v_lshlrev_b32_e32 v46, 16, v95
	v_and_b32_e32 v47, 0xffff0000, v95
	v_and_b32_e32 v53, 0xffff0000, v96
	v_lshlrev_b32_e32 v54, 16, v97
	v_and_b32_e32 v55, 0xffff0000, v97
	v_lshl_add_u64 v[48:49], s[4:5], 0, v[48:49]
	v_pk_fma_f32 v[46:47], v[50:51], v[76:77], v[46:47] op_sel_hi:[1,0,1]
	v_pk_fma_f32 v[42:43], v[42:43], v[76:77], v[54:55] op_sel_hi:[1,0,1]
	v_pk_fma_f32 v[40:41], v[40:41], v[76:77], v[52:53] op_sel_hi:[1,0,1]
	v_lshl_add_u64 v[48:49], v[48:49], 0, v[120:121]
	flat_store_dwordx4 v[48:49], v[44:47]
	flat_store_dwordx4 v[48:49], v[40:43] offset:16
	s_nop 0
	v_lshlrev_b32_e32 v44, 16, v100
	v_lshlrev_b32_e32 v40, 16, v98
	v_and_b32_e32 v41, 0xffff0000, v98
	v_lshlrev_b32_e32 v42, 16, v99
	v_and_b32_e32 v43, 0xffff0000, v99
	v_and_b32_e32 v45, 0xffff0000, v100
	v_lshlrev_b32_e32 v46, 16, v101
	v_and_b32_e32 v47, 0xffff0000, v101
	v_pk_fma_f32 v[38:39], v[38:39], v[76:77], v[42:43] op_sel_hi:[1,0,1]
	v_pk_fma_f32 v[36:37], v[36:37], v[76:77], v[40:41] op_sel_hi:[1,0,1]
	v_pk_fma_f32 v[28:29], v[28:29], v[76:77], v[44:45] op_sel_hi:[1,0,1]
	v_pk_fma_f32 v[30:31], v[30:31], v[76:77], v[46:47] op_sel_hi:[1,0,1]
	flat_store_dwordx4 v[48:49], v[36:39] offset:512
	flat_store_dwordx4 v[48:49], v[28:31] offset:528
	s_nop 0
	v_lshlrev_b32_e32 v36, 16, v104
	v_lshlrev_b32_e32 v28, 16, v102
	v_and_b32_e32 v29, 0xffff0000, v102
	v_pk_fma_f32 v[28:29], v[32:33], v[80:81], v[28:29] op_sel_hi:[1,0,1]
	v_lshlrev_b64 v[32:33], 13, v[82:83]
	v_lshlrev_b32_e32 v30, 16, v103
	v_and_b32_e32 v31, 0xffff0000, v103
	v_and_b32_e32 v37, 0xffff0000, v104
	v_lshlrev_b32_e32 v38, 16, v105
	v_and_b32_e32 v39, 0xffff0000, v105
	v_lshl_add_u64 v[32:33], s[4:5], 0, v[32:33]
	v_pk_fma_f32 v[30:31], v[34:35], v[80:81], v[30:31] op_sel_hi:[1,0,1]
	v_pk_fma_f32 v[26:27], v[26:27], v[80:81], v[38:39] op_sel_hi:[1,0,1]
	v_pk_fma_f32 v[24:25], v[24:25], v[80:81], v[36:37] op_sel_hi:[1,0,1]
	v_lshl_add_u64 v[32:33], v[32:33], 0, v[120:121]
	flat_store_dwordx4 v[32:33], v[28:31]
	flat_store_dwordx4 v[32:33], v[24:27] offset:16
	s_nop 0
	v_lshlrev_b32_e32 v28, 16, v108
	v_lshlrev_b32_e32 v24, 16, v106
	v_and_b32_e32 v25, 0xffff0000, v106
	v_lshlrev_b32_e32 v26, 16, v107
	v_and_b32_e32 v27, 0xffff0000, v107
	v_and_b32_e32 v29, 0xffff0000, v108
	v_lshlrev_b32_e32 v30, 16, v109
	v_and_b32_e32 v31, 0xffff0000, v109
	v_pk_fma_f32 v[22:23], v[22:23], v[80:81], v[26:27] op_sel_hi:[1,0,1]
	v_pk_fma_f32 v[20:21], v[20:21], v[80:81], v[24:25] op_sel_hi:[1,0,1]
	v_pk_fma_f32 v[12:13], v[12:13], v[80:81], v[28:29] op_sel_hi:[1,0,1]
	v_pk_fma_f32 v[14:15], v[14:15], v[80:81], v[30:31] op_sel_hi:[1,0,1]
	flat_store_dwordx4 v[32:33], v[20:23] offset:512
	flat_store_dwordx4 v[32:33], v[12:15] offset:528
	s_nop 0
	v_lshlrev_b32_e32 v20, 16, v112
	v_lshlrev_b32_e32 v12, 16, v110
	v_and_b32_e32 v13, 0xffff0000, v110
	v_pk_fma_f32 v[12:13], v[16:17], v[68:69], v[12:13] op_sel_hi:[1,0,1]
	v_lshlrev_b64 v[16:17], 13, v[84:85]
	v_lshlrev_b32_e32 v14, 16, v111
	v_and_b32_e32 v15, 0xffff0000, v111
	v_and_b32_e32 v21, 0xffff0000, v112
	v_lshlrev_b32_e32 v22, 16, v113
	v_and_b32_e32 v23, 0xffff0000, v113
	v_lshl_add_u64 v[16:17], s[4:5], 0, v[16:17]
	v_pk_fma_f32 v[14:15], v[18:19], v[68:69], v[14:15] op_sel_hi:[1,0,1]
	v_pk_fma_f32 v[10:11], v[10:11], v[68:69], v[22:23] op_sel_hi:[1,0,1]
	v_pk_fma_f32 v[8:9], v[8:9], v[68:69], v[20:21] op_sel_hi:[1,0,1]
	v_lshl_add_u64 v[16:17], v[16:17], 0, v[120:121]
	flat_store_dwordx4 v[16:17], v[12:15]
	flat_store_dwordx4 v[16:17], v[8:11] offset:16
	s_nop 0
	v_lshlrev_b32_e32 v12, 16, v66
	v_lshlrev_b32_e32 v8, 16, v64
	v_and_b32_e32 v9, 0xffff0000, v64
	v_lshlrev_b32_e32 v10, 16, v65
	v_and_b32_e32 v11, 0xffff0000, v65
	v_and_b32_e32 v13, 0xffff0000, v66
	v_lshlrev_b32_e32 v14, 16, v67
	v_and_b32_e32 v15, 0xffff0000, v67
	v_pk_fma_f32 v[6:7], v[6:7], v[68:69], v[10:11] op_sel_hi:[1,0,1]
	v_pk_fma_f32 v[4:5], v[4:5], v[68:69], v[8:9] op_sel_hi:[1,0,1]
	v_pk_fma_f32 v[2:3], v[2:3], v[68:69], v[14:15] op_sel_hi:[1,0,1]
	v_pk_fma_f32 v[0:1], v[0:1], v[68:69], v[12:13] op_sel_hi:[1,0,1]
	flat_store_dwordx4 v[16:17], v[4:7] offset:512
	flat_store_dwordx4 v[16:17], v[0:3] offset:528
	s_cbranch_vccnz .LBB0_950
	s_andn2_b64 vcc, exec, s[6:7]
	s_cbranch_vccnz .LBB0_949
	s_barrier
	s_branch .LBB0_949
